# G4 epilogue regenerated: WoutT B-tile column remap + DPP exchanges, x loads/out stores/U2 stores cover 8 rows x 128B, next x loads issued before stores
# speedup vs baseline: 1.0079x; 1.0079x over previous
; #define PG8_STAGE(bufoff, gbase, voff) do { _Pragma("unroll") for (int _i = 0; _i < 2; ++_i) \
;         __builtin_amdgcn_global_load_lds((const unsigned*)((const char*)(gbase) + (voff)[_i]), (PG8_LAS unsigned*)(lds + (bufoff) + ldsw + _i * 8192), 16, 0, 0); } while (0)
; #define PG8_WAIT_V(n) asm volatile("s_waitcnt vmcnt(" #n ")" ::: "memory")
; #define PG8_BAR __builtin_amdgcn_s_barrier()
; template <class Epi, class Sched, bool ALIGN_EPI = false, bool SP2 = false>
; __device__ __forceinline__ void gemm_phase(PG8_LAS unsigned char* lds, const Gemm g, const Sched& S, const Epi& E) {
;     ...
;     for (int i = 0; i < 2; ++i) { int R, C; stage_rc(tid * 16 + i * 8192, R, C); const int Rb = Epi::PERM ? ((R & ~31) + perm32(R & 31)) : R;
;         voffA[i] = (unsigned)(R * K + C) * 2u; voffB[i] = (unsigned)(Rb * K + C) * 2u; }
;     const size_t kstep = (size_t)(BK * 2);
;     const size_t hstep = (size_t)HALF * K * 2;
;     const size_t tstep = 2 * hstep;
;     const unsigned ldsw = (unsigned)wid * 1024u;
;     const int aoff = lds_byte(wr * 64 + fr, fq * 8), boff = lds_byte(wc * 32 + fr, fq * 8);
;     ...
;     const char* cA = (const char*)g.A + (size_t)cur.pm * tstep; const char* cB = (const char*)g.Bt + (size_t)cur.pn * tstep;
;     S.a_ready(cur);
;     if constexpr (SP2) {
;         PG8_STAGE(PG8_SB(0, 0), cB, voffB); PG8_STAGE(PG8_SB(0, 1), cB + hstep, voffB); PG8_STAGE(PG8_SA(0, 0), cA, voffA); PG8_STAGE(PG8_SA(0, 1), cA + hstep, voffA);
;         if (wr == 1) PG8_BAR;
;         PG8_WAIT_V(2); PG8_BAR;
;         PG8_STAGE(PG8_SB(1, 0), cB + kstep, voffB); PG8_STAGE(PG8_SA(1, 0), cA + kstep, voffA); PG8_STAGE(PG8_SB(1, 1), cB + hstep + kstep, voffB);
;         PG8_WAIT_V(6); PG8_BAR;
.LBB0_638:
	s_or_b64 exec, exec, s[2:3]
	v_readlane_b32 s12, v254, 56
	v_readlane_b32 s4, v251, 0
	v_readlane_b32 s13, v254, 57
	v_readlane_b32 s6, v251, 2
	v_readlane_b32 s7, v251, 3
	v_readlane_b32 s10, v251, 6
	v_readlane_b32 s11, v251, 7
	s_lshl_b64 s[2:3], s[12:13], 12
	v_readlane_b32 s8, v251, 4
	s_mov_b64 s[6:7], s[10:11]
	v_readlane_b32 s5, v251, 1
	v_readlane_b32 s9, v251, 5
	s_add_u32 s8, s6, s2
	s_addc_u32 s9, s7, s3
	v_readlane_b32 s2, v251, 52
	v_readlane_b32 s4, v254, 54
	v_readlane_b32 s5, v254, 55
	s_add_u32 s10, s2, s4
	v_readlane_b32 s2, v251, 53
	s_addc_u32 s11, s2, s5
	s_lshl_b64 s[2:3], s[12:13], 2
	v_readlane_b32 s4, v251, 48
	s_add_u32 s12, s4, s2
	v_readlane_b32 s2, v251, 49
	v_mov_b32_e32 v8, v188
	s_waitcnt lgkmcnt(0)
	s_barrier
	s_addc_u32 s13, s2, s3
	s_and_b64 vcc, exec, s[0:1]
	v_readfirstlane_b32 s6, v8
	s_cbranch_vccnz .LBB0_674
	v_lshlrev_b32_e32 v0, 4, v8
	v_add_u32_e32 v3, 0x2000, v0
	v_ashrrev_i32_e32 v2, 31, v3
	v_lshrrev_b32_e32 v2, 22, v2
	v_add_u32_e32 v2, v3, v2
	v_ashrrev_i32_e32 v2, 10, v2
	v_mul_i32_i24_e32 v4, 0x400, v2
	v_sub_u32_e32 v3, v3, v4
	v_lshrrev_b32_e32 v4, 4, v3
	v_bitop3_b32 v4, v4, v3, 32 bitop3:0x6c
	v_ashrrev_i32_e32 v3, 31, v4
	v_lshrrev_b32_e32 v3, 26, v3
	v_add_u32_e32 v5, v4, v3
	v_lshlrev_b32_e32 v6, 3, v2
	v_ashrrev_i32_e32 v3, 6, v5
	v_and_b32_e32 v6, -16, v6
	v_add_u32_e32 v6, v3, v6
	v_and_b32_e32 v7, 3, v3
	s_mov_b32 s2, 0x1fffe0
	v_lshrrev_b32_e32 v9, 2, v6
	v_lshlrev_b32_e32 v10, 1, v6
	v_and_b32_e32 v5, 0xc0, v5
	v_and_or_b32 v7, v6, s2, v7
	v_and_b32_e32 v9, 4, v9
	v_and_b32_e32 v10, 24, v10
	v_sub_u32_e32 v4, v4, v5
	v_or3_b32 v7, v7, v9, v10
	v_lshlrev_b32_e32 v9, 5, v2
	v_ashrrev_i16_sdwa v4, v189, sext(v4) dst_sel:DWORD dst_unused:UNUSED_PAD src0_sel:DWORD src1_sel:BYTE_0
	v_and_b32_e32 v9, 32, v9
	v_bfe_i32 v4, v4, 0, 16
	v_add_lshl_u32 v5, v9, v4, 1
	v_lshl_add_u32 v146, v7, 11, v5
	v_lshl_add_u32 v148, v6, 11, v5
	v_bfe_i32 v5, v8, 27, 1
	v_lshrrev_b32_e32 v5, 22, v5
	v_add_u32_e32 v5, v0, v5
	v_and_b32_e32 v5, 0xfffffc00, v5
	v_sub_u32_e32 v0, v0, v5
	v_lshrrev_b32_e32 v5, 4, v0
	v_ashrrev_i32_e32 v6, 31, v8
	v_bitop3_b32 v0, v5, v0, 32 bitop3:0x6c
	v_lshrrev_b32_e32 v6, 26, v6
	v_ashrrev_i32_e32 v5, 31, v0
	v_add_u32_e32 v6, v8, v6
	v_lshrrev_b32_e32 v5, 26, v5
	v_ashrrev_i32_e32 v6, 6, v6
	v_add_u32_e32 v7, v0, v5
	v_lshlrev_b32_e32 v9, 3, v6
	v_ashrrev_i32_e32 v5, 6, v7
	v_and_b32_e32 v9, -16, v9
	v_add_u32_e32 v9, v5, v9
	v_and_b32_e32 v10, 3, v5
	v_lshrrev_b32_e32 v11, 2, v9
	v_lshlrev_b32_e32 v12, 1, v9
	v_and_b32_e32 v7, 0xc0, v7
	v_and_or_b32 v10, v9, s2, v10
	v_and_b32_e32 v11, 4, v11
	v_and_b32_e32 v12, 24, v12
	v_sub_u32_e32 v0, v0, v7
	s_ashr_i32 s7, s6, 6
	v_or3_b32 v10, v10, v11, v12
	v_lshlrev_b32_e32 v11, 5, v6
	v_ashrrev_i16_sdwa v0, v189, sext(v0) dst_sel:DWORD dst_unused:UNUSED_PAD src0_sel:DWORD src1_sel:BYTE_0
	s_lshl_b32 s33, s7, 10
	v_and_b32_e32 v11, 32, v11
	v_bfe_i32 v7, v0, 0, 16
	v_add_lshl_u32 v11, v11, v7, 1
	s_add_i32 s34, s33, 0
	v_readlane_b32 s2, v253, 39
	v_lshl_add_u32 v0, v10, 11, v11
	s_add_i32 m0, s34, 0x10000
	v_readlane_b32 s3, v253, 40
	v_lshl_add_u32 v150, v9, 11, v11
	s_add_i32 s35, s34, 0x2000
	s_add_i32 s36, s34, 0x4000
	s_add_i32 s37, s34, 0x6000
	s_ashr_i32 s16, s6, 8
	s_lshl_b32 s98, s16, 16
	v_add_u32_e32 v0, s98, v0
	s_add_i32 s99, s98, 0x20000
	v_add_u32_e32 v146, s99, v146
	global_load_lds_dwordx4 v0, s[2:3]
	s_add_i32 m0, s34, 0x12000
	s_nop 0
	global_load_lds_dwordx4 v146, s[2:3]
	v_readlane_b32 s2, v253, 32
	s_add_i32 m0, s34, 0x14000
	v_readlane_b32 s3, v253, 33
	s_nop 4
	s_sub_u32 s2, s2, 0x30000
	s_subb_u32 s3, s3, 0
	s_nop 0
	global_load_lds_dwordx4 v0, s[2:3]
	s_add_i32 m0, s34, 0x16000
	s_nop 0
	global_load_lds_dwordx4 v146, s[2:3]
	v_readlane_b32 s2, v253, 35
	s_mov_b32 m0, s34
	v_readlane_b32 s3, v253, 36
	s_nop 4
	global_load_lds_dwordx4 v150, s[2:3]
	s_mov_b32 m0, s35
	s_nop 0
	global_load_lds_dwordx4 v148, s[2:3]
	v_readlane_b32 s2, v253, 37
	s_mov_b32 m0, s36
	v_readlane_b32 s3, v253, 38
	s_nop 4
	global_load_lds_dwordx4 v150, s[2:3]
	s_mov_b32 m0, s37
	s_nop 0
	global_load_lds_dwordx4 v148, s[2:3]
	v_readlane_b32 s2, v254, 56
	v_readlane_b32 s3, v254, 57
	s_lshl_b64 s[4:5], s[2:3], 10
	s_cmp_eq_u32 s16, 1
	s_cselect_b64 s[2:3], -1, 0
	s_cmp_lg_u32 s16, 1
	s_cbranch_scc1 .LBB0_641
	s_barrier
.LBB0_641:
	s_lshl_b64 s[4:5], s[4:5], 2
	v_bfe_u32 v18, v8, 4, 2
	s_add_u32 s14, s52, s4
	v_and_b32_e32 v9, 15, v8
	v_lshlrev_b32_e32 v19, 4, v18
	v_lshlrev_b32_e32 v8, 2, v8
	s_addc_u32 s15, s53, s5
	v_lshl_or_b32 v186, s16, 6, v9
	v_lshl_or_b32 v9, v9, 6, v19
	s_lshl_b32 s4, s16, 13
	v_and_b32_e32 v8, 32, v8
	v_readlane_b32 s28, v253, 39
	v_bitop3_b32 v19, v9, s4, v8 bitop3:0xde
	s_lshl_b32 s4, s7, 5
	v_readlane_b32 s29, v253, 40
	s_and_b32 s7, s4, 0x60
	v_mov_b32_e32 v147, v1
	v_lshl_add_u64 v[10:11], s[28:29], 0, v[0:1]
	v_readlane_b32 s26, v253, 35
	s_lshl_b32 s4, s7, 7
	v_lshl_add_u64 v[12:13], s[28:29], 0, v[146:147]
	v_mov_b32_e32 v151, v1
	v_readlane_b32 s27, v253, 36
	v_bitop3_b32 v187, v9, s4, v8 bitop3:0xde
	s_add_i32 m0, s34, 0x18000
	v_lshl_add_u64 v[8:9], v[10:11], 0, s[84:85]
	v_lshl_add_u64 v[14:15], s[26:27], 0, v[150:151]
	v_mov_b32_e32 v149, v1
	s_waitcnt vmcnt(2)
	s_barrier
	global_load_lds_dwordx4 v[8:9], off
	v_lshl_add_u64 v[8:9], v[12:13], 0, s[84:85]
	s_add_i32 m0, s34, 0x1a000
	s_add_i32 s38, s34, 0x8000
	v_lshl_add_u64 v[16:17], s[26:27], 0, v[148:149]
	global_load_lds_dwordx4 v[8:9], off
	v_lshl_add_u64 v[8:9], v[14:15], 0, s[84:85]
	s_mov_b32 m0, s38
	s_add_i32 s39, s34, 0xa000
	v_readlane_b32 s4, v253, 41
	global_load_lds_dwordx4 v[8:9], off
	v_lshl_add_u64 v[8:9], v[16:17], 0, s[84:85]
	s_mov_b32 m0, s39
	v_readlane_b32 s5, v253, 42
	global_load_lds_dwordx4 v[8:9], off
	s_add_i32 m0, s34, 0x1c000
	s_sub_u32 s4, s4, 0x30000
	s_subb_u32 s5, s5, 0
	v_lshl_add_u64 v[8:9], s[4:5], 0, v[0:1]
	global_load_lds_dwordx4 v[8:9], off
	v_lshl_add_u64 v[8:9], s[4:5], 0, v[146:147]
	s_add_i32 m0, s34, 0x1e000
	s_cmpk_lt_u32 s6, 0x100
	global_load_lds_dwordx4 v[8:9], off
	v_lshlrev_b32_e32 v8, 14, v6
	v_and_b32_e32 v8, 0xffff8000, v8
	v_lshl_add_u32 v5, v5, 11, v8
	v_and_b32_e32 v6, 1, v6
	v_lshl_or_b32 v5, v6, 6, v5
	v_lshl_add_u32 v152, v7, 1, v5
	v_lshlrev_b32_e32 v5, 14, v2
	v_and_b32_e32 v5, 0xffff8000, v5
	s_waitcnt vmcnt(6)
	v_lshl_add_u32 v3, v3, 11, v5
	v_and_b32_e32 v2, 1, v2
	v_lshl_or_b32 v199, v18, 3, s7
	v_lshl_or_b32 v2, v2, 6, v3
	v_readlane_b32 s6, v253, 10
	s_cselect_b64 s[16:17], -1, 0
	s_mov_b32 s40, 0
	v_cmp_eq_u32_e64 s[4:5], 0, v18
	v_mov_b32_e32 v153, v1
	v_lshl_add_u32 v154, v4, 1, v2
	v_mov_b32_e32 v155, v1
	v_add_u32_e32 v200, 0, v19
	v_readlane_b32 s41, v252, 35
	s_mov_b32 s42, s6
	s_barrier
	v_readlane_b32 s7, v253, 11
	s_branch .LBB0_644

; #define PG8_STAGE(bufoff, gbase, voff) do { _Pragma("unroll") for (int _i = 0; _i < 2; ++_i) \
;         __builtin_amdgcn_global_load_lds((const unsigned*)((const char*)(gbase) + (voff)[_i]), (PG8_LAS unsigned*)(lds + (bufoff) + ldsw + _i * 8192), 16, 0, 0); } while (0)
; #define PG8_LDA(dst, b, h) do { _Pragma("unroll") for (int m = 0; m < 4; ++m) _Pragma("unroll") for (int k = 0; k < 2; ++k) dst[m][k] = *(const PG8_LAS bf16x8*)(lds + PG8_SA(b, h) + aoff + m * 2048 + k * 1024); } while (0)
; #define PG8_LDB(dst, b, h) do { _Pragma("unroll") for (int n = 0; n < 2; ++n) _Pragma("unroll") for (int k = 0; k < 2; ++k) dst[n][k] = *(const PG8_LAS bf16x8*)(lds + PG8_SB(b, h) + boff + n * 2048 + k * 1024); } while (0)
; #define PG8_MMA(ai, bj, At, Bt) do { __builtin_amdgcn_s_setprio(1); _Pragma("unroll") for (int m = 0; m < 4; ++m) _Pragma("unroll") for (int n = 0; n < 2; ++n) _Pragma("unroll") for (int k = 0; k < 2; ++k) \
;         acc[ai][bj][m][n] = __builtin_amdgcn_mfma_f32_16x16x32_bf16(Bt[n][k], At[m][k], acc[ai][bj][m][n], 0, 0, 0); __builtin_amdgcn_s_setprio(0); } while (0)
; #define PG8_WAIT_V(n) asm volatile("s_waitcnt vmcnt(" #n ")" ::: "memory")
; #define PG8_WAIT_L(n) asm volatile("s_waitcnt lgkmcnt(" #n ")" ::: "memory")
; template <class Epi, class Sched, bool ALIGN_EPI = false, bool SP2 = false>
; __device__ __forceinline__ void gemm_phase(PG8_LAS unsigned char* lds, const Gemm g, const Sched& S, const Epi& E) {
;     ...
;             const bool last = (t == nt - 2);
;             const char* a1 = cA + (size_t)(t + 1) * kstep;
;             const char* a2 = last ? nA : cA + (size_t)(t + 2) * kstep; const char* b2 = last ? nB : cB + (size_t)(t + 2) * kstep;
;             const char* a3 = a2 + kstep; const char* b3 = b2 + kstep;
;             if (last && has_next) S.a_ready(nxt);
;             if constexpr (SP2) {
;             PG8_LDB(B0, 0, 0); PG8_LDB(B1, 0, 1); PG8_SCHED; PG8_LDA(At, 0, 0); PG8_STAGE(PG8_SA(1, 1), a1 + hstep, voffA);
;             PG8_WAIT_V(8); PG8_WAIT_L(0); PG8_BAR; PG8_MMA(0, 0, At, B0); PG8_MMA(0, 1, At, B1); PG8_BAR; PG8_SCHED;
;             PG8_LDA(At, 0, 1); PG8_STAGE(PG8_SB(0, 0), b2, voffB); PG8_STAGE(PG8_SB(0, 1), b2 + hstep, voffB); PG8_STAGE(PG8_SA(0, 0), a2, voffA);
;             PG8_WAIT_V(8); PG8_WAIT_L(0); PG8_BAR; PG8_MMA(1, 0, At, B0); PG8_MMA(1, 1, At, B1); PG8_BAR; PG8_SCHED;
.LBB0_651:
	s_add_u32 s28, s26, 0xfffc0080
	s_addc_u32 s29, s27, -1
	s_add_i32 s48, 0, 0x10000
	s_cmp_eq_u32 s47, 12
	s_cselect_b32 s31, s21, s29
	s_cselect_b32 s30, s43, s28
	s_cselect_b32 s29, s19, s46
	s_cselect_b32 s28, s44, s45
	s_add_i32 s50, 0, 0x14000
	v_add_u32_e32 v94, s48, v187
	v_add_u32_e32 v160, s50, v187
	ds_read_b128 v[82:85], v94
	ds_read_b128 v[86:89], v94 offset:1024
	ds_read_b128 v[90:93], v94 offset:2048
	ds_read_b128 v[94:97], v94 offset:3072
	ds_read_b128 v[156:159], v160
	ds_read_b128 v[178:181], v160 offset:1024
	ds_read_b128 v[182:185], v160 offset:2048
	ds_read_b128 v[202:205], v160 offset:3072
	v_lshl_add_u64 v[160:161], s[26:27], 0, v[152:153]
	s_add_i32 m0, s34, 0xc000
	ds_read_b128 v[206:209], v200
	ds_read_b128 v[210:213], v200 offset:1024
	ds_read_b128 v[214:217], v200 offset:2048
	ds_read_b128 v[218:221], v200 offset:3072
	ds_read_b128 v[222:225], v200 offset:4096
	ds_read_b128 v[226:229], v200 offset:5120
	ds_read_b128 v[230:233], v200 offset:6144
	ds_read_b128 v[234:237], v200 offset:7168
	global_load_lds_dwordx4 v[160:161], off
	v_lshl_add_u64 v[160:161], s[26:27], 0, v[154:155]
	s_add_i32 m0, s34, 0xe000
	s_nop 0
	global_load_lds_dwordx4 v[160:161], off
	s_waitcnt vmcnt(8)
	s_waitcnt lgkmcnt(0)
	s_barrier
	s_setprio 1
	s_waitcnt lgkmcnt(0)
	v_mfma_f32_16x16x32_bf16 v[142:145], v[82:85], v[206:209], v[142:145]
	v_mfma_f32_16x16x32_bf16 v[138:141], v[90:93], v[206:209], v[138:141]
	v_mfma_f32_16x16x32_bf16 v[126:129], v[82:85], v[214:217], v[126:129]
	v_mfma_f32_16x16x32_bf16 v[122:125], v[90:93], v[214:217], v[122:125]
	v_mfma_f32_16x16x32_bf16 v[110:113], v[82:85], v[222:225], v[110:113]
	v_mfma_f32_16x16x32_bf16 v[106:109], v[90:93], v[222:225], v[106:109]
	v_mfma_f32_16x16x32_bf16 v[78:81], v[82:85], v[230:233], v[78:81]
	v_mfma_f32_16x16x32_bf16 v[74:77], v[90:93], v[230:233], v[74:77]
	v_mfma_f32_16x16x32_bf16 v[142:145], v[86:89], v[210:213], v[142:145]
	v_mfma_f32_16x16x32_bf16 v[138:141], v[94:97], v[210:213], v[138:141]
	v_mfma_f32_16x16x32_bf16 v[126:129], v[86:89], v[218:221], v[126:129]
	v_mfma_f32_16x16x32_bf16 v[122:125], v[94:97], v[218:221], v[122:125]
	v_mfma_f32_16x16x32_bf16 v[110:113], v[86:89], v[226:229], v[110:113]
	v_mfma_f32_16x16x32_bf16 v[106:109], v[94:97], v[226:229], v[106:109]
	v_mfma_f32_16x16x32_bf16 v[78:81], v[86:89], v[234:237], v[78:81]
	v_mfma_f32_16x16x32_bf16 v[74:77], v[94:97], v[234:237], v[74:77]
	s_setprio 0
	s_setprio 1
	v_mfma_f32_16x16x32_bf16 v[134:137], v[156:159], v[206:209], v[134:137]
	v_mfma_f32_16x16x32_bf16 v[130:133], v[182:185], v[206:209], v[130:133]
	v_mfma_f32_16x16x32_bf16 v[118:121], v[156:159], v[214:217], v[118:121]
	v_mfma_f32_16x16x32_bf16 v[114:117], v[182:185], v[214:217], v[114:117]
	v_mfma_f32_16x16x32_bf16 v[102:105], v[156:159], v[222:225], v[102:105]
	v_mfma_f32_16x16x32_bf16 v[98:101], v[182:185], v[222:225], v[98:101]
	v_mfma_f32_16x16x32_bf16 v[70:73], v[156:159], v[230:233], v[70:73]
	v_mfma_f32_16x16x32_bf16 v[66:69], v[182:185], v[230:233], v[66:69]
	v_mfma_f32_16x16x32_bf16 v[134:137], v[178:181], v[210:213], v[134:137]
	v_mfma_f32_16x16x32_bf16 v[130:133], v[202:205], v[210:213], v[130:133]
	v_mfma_f32_16x16x32_bf16 v[118:121], v[178:181], v[218:221], v[118:121]
	v_mfma_f32_16x16x32_bf16 v[114:117], v[202:205], v[218:221], v[114:117]
	v_mfma_f32_16x16x32_bf16 v[102:105], v[178:181], v[226:229], v[102:105]
	v_mfma_f32_16x16x32_bf16 v[98:101], v[202:205], v[226:229], v[98:101]
	v_mfma_f32_16x16x32_bf16 v[70:73], v[178:181], v[234:237], v[70:73]
	v_mfma_f32_16x16x32_bf16 v[66:69], v[202:205], v[234:237], v[66:69]
	s_setprio 0
	s_barrier
	s_add_i32 s48, s48, s33
	v_lshl_add_u64 v[160:161], s[28:29], 0, v[0:1]
	s_mov_b32 m0, s48
	ds_read_b128 v[206:209], v200 offset:16384
	ds_read_b128 v[210:213], v200 offset:17408
	ds_read_b128 v[214:217], v200 offset:18432
	ds_read_b128 v[218:221], v200 offset:19456
	ds_read_b128 v[222:225], v200 offset:20480
	ds_read_b128 v[226:229], v200 offset:21504
	ds_read_b128 v[230:233], v200 offset:22528
	ds_read_b128 v[234:237], v200 offset:23552
	global_load_lds_dwordx4 v[160:161], off
	s_add_i32 m0, s48, 0x2000
	s_add_u32 s48, s28, 0x10000
	v_lshl_add_u64 v[162:163], s[28:29], 0, v[146:147]
	s_addc_u32 s49, s29, 0
	s_add_i32 s50, s50, s33
	global_load_lds_dwordx4 v[162:163], off
	v_lshl_add_u64 v[164:165], s[48:49], 0, v[0:1]
	s_mov_b32 m0, s50
	v_lshl_add_u64 v[190:191], s[30:31], 0, v[148:149]
	global_load_lds_dwordx4 v[164:165], off
	v_lshl_add_u64 v[164:165], s[48:49], 0, v[146:147]
	s_add_i32 m0, s50, 0x2000
	s_nop 0
	global_load_lds_dwordx4 v[164:165], off
	v_lshl_add_u64 v[164:165], s[30:31], 0, v[150:151]
	s_mov_b32 m0, s34
	s_nop 0
	global_load_lds_dwordx4 v[164:165], off
	s_mov_b32 m0, s35
	s_nop 0
	global_load_lds_dwordx4 v[190:191], off
	s_waitcnt vmcnt(8)
	s_waitcnt lgkmcnt(0)
	s_barrier
; #define PG8_STAGE(bufoff, gbase, voff) do { _Pragma("unroll") for (int _i = 0; _i < 2; ++_i) \
;         __builtin_amdgcn_global_load_lds((const unsigned*)((const char*)(gbase) + (voff)[_i]), (PG8_LAS unsigned*)(lds + (bufoff) + ldsw + _i * 8192), 16, 0, 0); } while (0)
; #define PG8_LDA(dst, b, h) do { _Pragma("unroll") for (int m = 0; m < 4; ++m) _Pragma("unroll") for (int k = 0; k < 2; ++k) dst[m][k] = *(const PG8_LAS bf16x8*)(lds + PG8_SA(b, h) + aoff + m * 2048 + k * 1024); } while (0)
; #define PG8_LDB(dst, b, h) do { _Pragma("unroll") for (int n = 0; n < 2; ++n) _Pragma("unroll") for (int k = 0; k < 2; ++k) dst[n][k] = *(const PG8_LAS bf16x8*)(lds + PG8_SB(b, h) + boff + n * 2048 + k * 1024); } while (0)
; #define PG8_MMA(ai, bj, At, Bt) do { __builtin_amdgcn_s_setprio(1); _Pragma("unroll") for (int m = 0; m < 4; ++m) _Pragma("unroll") for (int n = 0; n < 2; ++n) _Pragma("unroll") for (int k = 0; k < 2; ++k) \
;         acc[ai][bj][m][n] = __builtin_amdgcn_mfma_f32_16x16x32_bf16(Bt[n][k], At[m][k], acc[ai][bj][m][n], 0, 0, 0); __builtin_amdgcn_s_setprio(0); } while (0)
; #define PG8_WAIT_V(n) asm volatile("s_waitcnt vmcnt(" #n ")" ::: "memory")
; #define PG8_WAIT_L(n) asm volatile("s_waitcnt lgkmcnt(" #n ")" ::: "memory")
; #define PG8_BAR __builtin_amdgcn_s_barrier()
; #define PG8_SCHED __builtin_amdgcn_sched_barrier(0)
; template <class Epi, class Sched, bool ALIGN_EPI = false, bool SP2 = false>
; __device__ __forceinline__ void gemm_phase(PG8_LAS unsigned char* lds, const Gemm g, const Sched& S, const Epi& E) {
;     ...
;             PG8_WAIT_V(8); PG8_WAIT_L(0); PG8_BAR; PG8_MMA(1, 0, At, B0); PG8_MMA(1, 1, At, B1); PG8_BAR; PG8_SCHED;
;             PG8_LDB(B0, 1, 0); PG8_LDB(B1, 1, 1); PG8_SCHED; PG8_LDA(At, 1, 0); PG8_STAGE(PG8_SA(0, 1), a2 + hstep, voffA);
;             PG8_WAIT_V(8); PG8_WAIT_L(0); PG8_BAR; PG8_MMA(0, 0, At, B0); PG8_MMA(0, 1, At, B1); PG8_BAR; PG8_SCHED;
;             PG8_LDA(At, 1, 1); PG8_STAGE(PG8_SB(1, 0), b3, voffB); PG8_STAGE(PG8_SB(1, 1), b3 + hstep, voffB); PG8_STAGE(PG8_SA(1, 0), a3, voffA);
	s_setprio 1
	s_waitcnt lgkmcnt(0)
	v_mfma_f32_16x16x32_bf16 v[62:65], v[82:85], v[206:209], v[62:65]
	v_mfma_f32_16x16x32_bf16 v[58:61], v[90:93], v[206:209], v[58:61]
	v_mfma_f32_16x16x32_bf16 v[46:49], v[82:85], v[214:217], v[46:49]
	v_mfma_f32_16x16x32_bf16 v[42:45], v[90:93], v[214:217], v[42:45]
	v_mfma_f32_16x16x32_bf16 v[30:33], v[82:85], v[222:225], v[30:33]
	v_mfma_f32_16x16x32_bf16 v[26:29], v[90:93], v[222:225], v[26:29]
	v_mfma_f32_16x16x32_bf16 v[14:17], v[82:85], v[230:233], v[14:17]
	v_mfma_f32_16x16x32_bf16 v[10:13], v[90:93], v[230:233], v[10:13]
	v_mfma_f32_16x16x32_bf16 v[62:65], v[86:89], v[210:213], v[62:65]
	v_mfma_f32_16x16x32_bf16 v[58:61], v[94:97], v[210:213], v[58:61]
	v_mfma_f32_16x16x32_bf16 v[46:49], v[86:89], v[218:221], v[46:49]
	v_mfma_f32_16x16x32_bf16 v[42:45], v[94:97], v[218:221], v[42:45]
	v_mfma_f32_16x16x32_bf16 v[30:33], v[86:89], v[226:229], v[30:33]
	v_mfma_f32_16x16x32_bf16 v[26:29], v[94:97], v[226:229], v[26:29]
	v_mfma_f32_16x16x32_bf16 v[14:17], v[86:89], v[234:237], v[14:17]
	v_mfma_f32_16x16x32_bf16 v[10:13], v[94:97], v[234:237], v[10:13]
	s_setprio 0
	s_setprio 1
	v_mfma_f32_16x16x32_bf16 v[54:57], v[156:159], v[206:209], v[54:57]
	v_mfma_f32_16x16x32_bf16 v[50:53], v[182:185], v[206:209], v[50:53]
	v_mfma_f32_16x16x32_bf16 v[38:41], v[156:159], v[214:217], v[38:41]
	v_mfma_f32_16x16x32_bf16 v[34:37], v[182:185], v[214:217], v[34:37]
	v_mfma_f32_16x16x32_bf16 v[22:25], v[156:159], v[222:225], v[22:25]
	v_mfma_f32_16x16x32_bf16 v[18:21], v[182:185], v[222:225], v[18:21]
	v_mfma_f32_16x16x32_bf16 v[6:9], v[156:159], v[230:233], v[6:9]
	v_mfma_f32_16x16x32_bf16 v[2:5], v[182:185], v[230:233], v[2:5]
	v_mfma_f32_16x16x32_bf16 v[54:57], v[178:181], v[210:213], v[54:57]
	v_mfma_f32_16x16x32_bf16 v[50:53], v[202:205], v[210:213], v[50:53]
	v_mfma_f32_16x16x32_bf16 v[38:41], v[178:181], v[218:221], v[38:41]
	v_mfma_f32_16x16x32_bf16 v[34:37], v[202:205], v[218:221], v[34:37]
	v_mfma_f32_16x16x32_bf16 v[22:25], v[178:181], v[226:229], v[22:25]
	v_mfma_f32_16x16x32_bf16 v[18:21], v[202:205], v[226:229], v[18:21]
	v_mfma_f32_16x16x32_bf16 v[6:9], v[178:181], v[234:237], v[6:9]
	v_mfma_f32_16x16x32_bf16 v[2:5], v[202:205], v[234:237], v[2:5]
	s_setprio 0
	s_barrier
	s_add_i32 s48, 0, 0x18000
	s_add_i32 s49, 0, 0x1c000
	v_add_u32_e32 v94, s48, v187
	v_add_u32_e32 v201, s49, v187
	ds_read_b128 v[82:85], v94
	ds_read_b128 v[86:89], v94 offset:1024
	ds_read_b128 v[90:93], v94 offset:2048
	ds_read_b128 v[94:97], v94 offset:3072
	ds_read_b128 v[156:159], v201
	ds_read_b128 v[178:181], v201 offset:1024
	ds_read_b128 v[182:185], v201 offset:2048
	ds_read_b128 v[202:205], v201 offset:3072
	s_add_u32 s30, s30, 0x40000
	s_addc_u32 s31, s31, 0
	s_mov_b32 m0, s36
	v_lshl_add_u64 v[238:239], s[30:31], 0, v[150:151]
	ds_read_b128 v[206:209], v200 offset:32768
	ds_read_b128 v[210:213], v200 offset:33792
	ds_read_b128 v[214:217], v200 offset:34816
	ds_read_b128 v[218:221], v200 offset:35840
	ds_read_b128 v[222:225], v200 offset:36864
	ds_read_b128 v[226:229], v200 offset:37888
	ds_read_b128 v[230:233], v200 offset:38912
	ds_read_b128 v[234:237], v200 offset:39936
	global_load_lds_dwordx4 v[238:239], off
	v_lshl_add_u64 v[238:239], s[30:31], 0, v[148:149]
	s_mov_b32 m0, s37
	s_nop 0
	global_load_lds_dwordx4 v[238:239], off
	s_waitcnt vmcnt(8)
	s_waitcnt lgkmcnt(0)
	s_barrier
	s_setprio 1
	s_waitcnt lgkmcnt(0)
	v_mfma_f32_16x16x32_bf16 v[142:145], v[82:85], v[206:209], v[142:145]
	v_mfma_f32_16x16x32_bf16 v[138:141], v[90:93], v[206:209], v[138:141]
	v_mfma_f32_16x16x32_bf16 v[126:129], v[82:85], v[214:217], v[126:129]
	v_mfma_f32_16x16x32_bf16 v[122:125], v[90:93], v[214:217], v[122:125]
	v_mfma_f32_16x16x32_bf16 v[110:113], v[82:85], v[222:225], v[110:113]
	v_mfma_f32_16x16x32_bf16 v[106:109], v[90:93], v[222:225], v[106:109]
	v_mfma_f32_16x16x32_bf16 v[78:81], v[82:85], v[230:233], v[78:81]
	v_mfma_f32_16x16x32_bf16 v[74:77], v[90:93], v[230:233], v[74:77]
	v_mfma_f32_16x16x32_bf16 v[142:145], v[86:89], v[210:213], v[142:145]
	v_mfma_f32_16x16x32_bf16 v[138:141], v[94:97], v[210:213], v[138:141]
	v_mfma_f32_16x16x32_bf16 v[126:129], v[86:89], v[218:221], v[126:129]
	v_mfma_f32_16x16x32_bf16 v[122:125], v[94:97], v[218:221], v[122:125]
	v_mfma_f32_16x16x32_bf16 v[110:113], v[86:89], v[226:229], v[110:113]
	v_mfma_f32_16x16x32_bf16 v[106:109], v[94:97], v[226:229], v[106:109]
	v_mfma_f32_16x16x32_bf16 v[78:81], v[86:89], v[234:237], v[78:81]
	v_mfma_f32_16x16x32_bf16 v[74:77], v[94:97], v[234:237], v[74:77]
	s_setprio 0
	s_setprio 1
	v_mfma_f32_16x16x32_bf16 v[134:137], v[156:159], v[206:209], v[134:137]
	v_mfma_f32_16x16x32_bf16 v[130:133], v[182:185], v[206:209], v[130:133]
	v_mfma_f32_16x16x32_bf16 v[118:121], v[156:159], v[214:217], v[118:121]
	v_mfma_f32_16x16x32_bf16 v[114:117], v[182:185], v[214:217], v[114:117]
	v_mfma_f32_16x16x32_bf16 v[102:105], v[156:159], v[222:225], v[102:105]
	v_mfma_f32_16x16x32_bf16 v[98:101], v[182:185], v[222:225], v[98:101]
	v_mfma_f32_16x16x32_bf16 v[70:73], v[156:159], v[230:233], v[70:73]
	v_mfma_f32_16x16x32_bf16 v[66:69], v[182:185], v[230:233], v[66:69]
	v_mfma_f32_16x16x32_bf16 v[134:137], v[178:181], v[210:213], v[134:137]
	v_mfma_f32_16x16x32_bf16 v[130:133], v[202:205], v[210:213], v[130:133]
	v_mfma_f32_16x16x32_bf16 v[118:121], v[178:181], v[218:221], v[118:121]
	v_mfma_f32_16x16x32_bf16 v[114:117], v[202:205], v[218:221], v[114:117]
	v_mfma_f32_16x16x32_bf16 v[102:105], v[178:181], v[226:229], v[102:105]
	v_mfma_f32_16x16x32_bf16 v[98:101], v[202:205], v[226:229], v[98:101]
	v_mfma_f32_16x16x32_bf16 v[70:73], v[178:181], v[234:237], v[70:73]
	v_mfma_f32_16x16x32_bf16 v[66:69], v[202:205], v[234:237], v[66:69]
	s_setprio 0
	s_barrier
; #define PG8_STAGE(bufoff, gbase, voff) do { _Pragma("unroll") for (int _i = 0; _i < 2; ++_i) \
;         __builtin_amdgcn_global_load_lds((const unsigned*)((const char*)(gbase) + (voff)[_i]), (PG8_LAS unsigned*)(lds + (bufoff) + ldsw + _i * 8192), 16, 0, 0); } while (0)
; #define PG8_LDA(dst, b, h) do { _Pragma("unroll") for (int m = 0; m < 4; ++m) _Pragma("unroll") for (int k = 0; k < 2; ++k) dst[m][k] = *(const PG8_LAS bf16x8*)(lds + PG8_SA(b, h) + aoff + m * 2048 + k * 1024); } while (0)
; #define PG8_WAIT_V(n) asm volatile("s_waitcnt vmcnt(" #n ")" ::: "memory")
; #define PG8_WAIT_L(n) asm volatile("s_waitcnt lgkmcnt(" #n ")" ::: "memory")
; #define PG8_BAR __builtin_amdgcn_s_barrier()
; #define PG8_SCHED __builtin_amdgcn_sched_barrier(0)
; template <class Epi, class Sched, bool ALIGN_EPI = false, bool SP2 = false>
; __device__ __forceinline__ void gemm_phase(PG8_LAS unsigned char* lds, const Gemm g, const Sched& S, const Epi& E) {
;     ...
;             PG8_LDA(At, 1, 1); PG8_STAGE(PG8_SB(1, 0), b3, voffB); PG8_STAGE(PG8_SB(1, 1), b3 + hstep, voffB); PG8_STAGE(PG8_SA(1, 0), a3, voffA);
;             PG8_WAIT_V(8); PG8_WAIT_L(0); PG8_BAR; PG8_MMA(1, 0, At, B0); PG8_MMA(1, 1, At, B1); PG8_BAR; PG8_SCHED;
;     DI void operator()(const f32x4 (&acc)[2][2][4][2], const Unit& u, int wr, int wc, int fr, int fq) const {
;         const int row0 = u.pm * 256 + wr * 64 + fr, col0 = u.pn * 256 + wc * 32 + 8 * fq;
;         const int b = (grow0 + u.pm * 256) >> 11;
;         f32x4 g[2][2], gm[2][2];
; #pragma unroll
;         for (int bj = 0; bj < 2; ++bj) { const int c = col0 + bj * 128; const float* gp = ada + (size_t)b * 6144 + 2048 + c; const float* sp = ada + (size_t)b * 6144 + 4096 + c;
;             g[bj][0] = *(const f32x4*)gp; g[bj][1] = *(const f32x4*)(gp + 4);
;             gm[bj][0] = *(const f32x4*)(g2 + c) * (*(const f32x4*)sp + 1.0f); gm[bj][1] = *(const f32x4*)(g2 + c + 4) * (*(const f32x4*)(sp + 4) + 1.0f); }
; #pragma unroll
;         for (int ai = 0; ai < 2; ++ai)
; #pragma unroll
;             for (int m = 0; m < 4; ++m) { const size_t r = (size_t)(row0 + ai * 128 + m * 16); float ss = 0.f;
; #pragma unroll
;                 for (int bj = 0; bj < 2; ++bj) { const size_t off = r * 1024 + col0 + bj * 128;
;                     f32x4 v0 = *(const f32x4*)(base + off), v1 = *(const f32x4*)(base + off + 4);
	s_add_i32 s30, s48, s33
	v_lshl_add_u64 v[160:161], v[160:161], 0, s[84:85]
	s_mov_b32 m0, s30
	ds_read_b128 v[206:209], v200 offset:49152
	ds_read_b128 v[210:213], v200 offset:50176
	ds_read_b128 v[214:217], v200 offset:51200
	ds_read_b128 v[218:221], v200 offset:52224
	ds_read_b128 v[222:225], v200 offset:53248
	ds_read_b128 v[226:229], v200 offset:54272
	ds_read_b128 v[230:233], v200 offset:55296
	ds_read_b128 v[234:237], v200 offset:56320
	global_load_lds_dwordx4 v[160:161], off
	s_add_i32 m0, s30, 0x2000
	s_add_u32 s28, s28, 0x10080
	v_lshl_add_u64 v[160:161], v[162:163], 0, s[84:85]
	s_addc_u32 s29, s29, 0
	s_add_i32 s30, s49, s33
	global_load_lds_dwordx4 v[160:161], off
	v_lshl_add_u64 v[160:161], s[28:29], 0, v[0:1]
	s_mov_b32 m0, s30
	s_nop 0
	global_load_lds_dwordx4 v[160:161], off
	v_lshl_add_u64 v[160:161], s[28:29], 0, v[146:147]
	s_add_i32 m0, s30, 0x2000
	s_nop 0
	global_load_lds_dwordx4 v[160:161], off
	v_lshl_add_u64 v[160:161], v[164:165], 0, s[84:85]
	s_mov_b32 m0, s38
	s_nop 0
	global_load_lds_dwordx4 v[160:161], off
	v_lshl_add_u64 v[160:161], v[190:191], 0, s[84:85]
	s_mov_b32 m0, s39
	s_nop 0
	global_load_lds_dwordx4 v[160:161], off
	s_waitcnt vmcnt(8)
	s_waitcnt lgkmcnt(0)
	s_barrier
	s_setprio 1
	s_waitcnt lgkmcnt(0)
	v_mfma_f32_16x16x32_bf16 v[62:65], v[82:85], v[206:209], v[62:65]
	v_mfma_f32_16x16x32_bf16 v[58:61], v[90:93], v[206:209], v[58:61]
	v_mfma_f32_16x16x32_bf16 v[46:49], v[82:85], v[214:217], v[46:49]
	v_mfma_f32_16x16x32_bf16 v[42:45], v[90:93], v[214:217], v[42:45]
	v_mfma_f32_16x16x32_bf16 v[30:33], v[82:85], v[222:225], v[30:33]
	v_mfma_f32_16x16x32_bf16 v[26:29], v[90:93], v[222:225], v[26:29]
	v_mfma_f32_16x16x32_bf16 v[14:17], v[82:85], v[230:233], v[14:17]
	v_mfma_f32_16x16x32_bf16 v[10:13], v[90:93], v[230:233], v[10:13]
	v_mfma_f32_16x16x32_bf16 v[62:65], v[86:89], v[210:213], v[62:65]
	v_mfma_f32_16x16x32_bf16 v[58:61], v[94:97], v[210:213], v[58:61]
	v_mfma_f32_16x16x32_bf16 v[46:49], v[86:89], v[218:221], v[46:49]
	v_mfma_f32_16x16x32_bf16 v[42:45], v[94:97], v[218:221], v[42:45]
	v_mfma_f32_16x16x32_bf16 v[30:33], v[86:89], v[226:229], v[30:33]
	v_mfma_f32_16x16x32_bf16 v[26:29], v[94:97], v[226:229], v[26:29]
	v_mfma_f32_16x16x32_bf16 v[14:17], v[86:89], v[234:237], v[14:17]
	v_mfma_f32_16x16x32_bf16 v[10:13], v[94:97], v[234:237], v[10:13]
	s_setprio 0
	s_setprio 1
	v_mfma_f32_16x16x32_bf16 v[54:57], v[156:159], v[206:209], v[54:57]
	v_mfma_f32_16x16x32_bf16 v[50:53], v[182:185], v[206:209], v[50:53]
	v_mfma_f32_16x16x32_bf16 v[38:41], v[156:159], v[214:217], v[38:41]
	v_mfma_f32_16x16x32_bf16 v[34:37], v[182:185], v[214:217], v[34:37]
	v_mfma_f32_16x16x32_bf16 v[22:25], v[156:159], v[222:225], v[22:25]
	v_mfma_f32_16x16x32_bf16 v[18:21], v[182:185], v[222:225], v[18:21]
	v_mfma_f32_16x16x32_bf16 v[6:9], v[156:159], v[230:233], v[6:9]
	v_mfma_f32_16x16x32_bf16 v[2:5], v[182:185], v[230:233], v[2:5]
	v_mfma_f32_16x16x32_bf16 v[54:57], v[178:181], v[210:213], v[54:57]
	v_mfma_f32_16x16x32_bf16 v[50:53], v[202:205], v[210:213], v[50:53]
	v_mfma_f32_16x16x32_bf16 v[38:41], v[178:181], v[218:221], v[38:41]
	v_mfma_f32_16x16x32_bf16 v[34:37], v[202:205], v[218:221], v[34:37]
	v_mfma_f32_16x16x32_bf16 v[22:25], v[178:181], v[226:229], v[22:25]
	v_mfma_f32_16x16x32_bf16 v[18:21], v[202:205], v[226:229], v[18:21]
	v_mfma_f32_16x16x32_bf16 v[6:9], v[178:181], v[234:237], v[6:9]
	v_mfma_f32_16x16x32_bf16 v[2:5], v[202:205], v[234:237], v[2:5]
	s_setprio 0
	s_barrier
	s_add_i32 s47, s47, 2
	s_add_u32 s26, s26, 0x100
	s_addc_u32 s27, s27, 0
	s_add_u32 s45, s45, 0x100
	s_addc_u32 s46, s46, 0
	s_cmp_gt_u32 s47, 13
	s_cbranch_scc0 .LBB0_651
	s_and_b64 vcc, exec, s[16:17]
	s_cbranch_vccz .LBB0_654
	s_barrier
.LBB0_654:
	s_lshl_b32 s19, s42, 8
	v_readlane_b32 s26, v254, 56
	s_add_i32 s21, s19, s26
	s_ashr_i32 s21, s21, 11
	s_mul_hi_i32 s26, s21, 0x6000
	s_mulk_i32 s21, 0x6000
	v_readlane_b32 s28, v251, 8
	v_readlane_b32 s29, v251, 9
	s_add_u32 s21, s28, s21
	s_addc_u32 s29, s29, s26
	v_add_u32_e32 v184, s19, v186
	v_lshl_or_b32 v182, s41, 8, v199
	v_readlane_b32 s27, v254, 57
	s_add_u32 s26, s21, 0x2000
	v_ashrrev_i32_e32 v185, 31, v184
	s_addc_u32 s27, s29, 0
	v_ashrrev_i32_e32 v183, 31, v182
	v_lshlrev_b64 v[84:85], 10, v[184:185]
	v_lshl_add_u64 v[156:157], v[84:85], 0, v[182:183]
	s_add_u32 s28, s21, 0x4000
	v_lshlrev_b64 v[90:91], 2, v[182:183]
	v_lshlrev_b64 v[92:93], 2, v[156:157]
	s_addc_u32 s29, s29, 0
	v_and_b32_e32 v218, 0x60, v199
	v_add_u32_e32 v182, v182, v218
	v_bfe_u32 v219, v184, 3, 1
	v_lshl_add_u32 v218, v184, 10, v182
	v_lshlrev_b32_e32 v156, 2, v218
	v_mov_b32_e32 v157, 0
	v_mul_u32_u24_e32 v220, 0x7ff0, v219
	v_sub_u32_e32 v156, v156, v220
	v_lshl_add_u64 v[156:157], s[14:15], 0, v[156:157]
	v_and_b32_e32 v218, 0xfffffff7, v184
	v_lshl_add_u32 v218, v218, 10, v182
	v_lshl_add_u32 v218, v219, 5, v218
	v_lshlrev_b32_e32 v158, 1, v218
	v_mov_b32_e32 v159, 0
	v_lshl_add_u64 v[158:159], s[10:11], 0, v[158:159]
	v_lshlrev_b32_e32 v160, 2, v184
	v_mov_b32_e32 v161, 0
	v_lshl_add_u64 v[160:161], s[12:13], 0, v[160:161]
	v_xor_b32_e32 v180, 16, v194
	v_lshlrev_b32_e32 v180, 2, v180
	v_xor_b32_e32 v181, 32, v194
	v_lshlrev_b32_e32 v181, 2, v181
	s_sub_u32 s100, s8, s14
	s_subb_u32 s101, s9, s15
	v_lshlrev_b32_e32 v178, 2, v182
	v_mov_b32_e32 v179, 0
	v_lshl_add_u64 v[190:191], s[26:27], 0, v[178:179]
	global_load_dwordx4 v[82:85], v[190:191], off
	global_load_dwordx4 v[86:89], v[190:191], off offset:16
	global_load_dwordx4 v[90:93], v[190:191], off offset:128
	global_load_dwordx4 v[94:97], v[190:191], off offset:144
	v_lshl_add_u64 v[190:191], s[28:29], 0, v[178:179]
	global_load_dwordx4 v[162:165], v[190:191], off
	global_load_dwordx4 v[182:185], v[190:191], off offset:16
	global_load_dwordx4 v[234:237], v[190:191], off offset:128
	global_load_dwordx4 v[244:247], v[190:191], off offset:144
	v_lshl_add_u64 v[190:191], s[62:63], 0, v[178:179]
	global_load_dwordx4 v[202:205], v[190:191], off
	global_load_dwordx4 v[206:209], v[190:191], off offset:16
	global_load_dwordx4 v[210:213], v[190:191], off offset:128
	global_load_dwordx4 v[214:217], v[190:191], off offset:144
	s_mov_b64 s[98:99], 0x8000
	v_lshl_add_u64 v[178:179], v[156:157], 0, s[98:99]
	global_load_dwordx4 v[218:221], v[156:157], off
	global_load_dwordx4 v[222:225], v[178:179], off
	global_load_dwordx4 v[226:229], v[156:157], off offset:128
	global_load_dwordx4 v[230:233], v[178:179], off offset:128
	s_waitcnt vmcnt(4)
; DI unsigned pk2(float lo, float hi) { return pg8::cvt_pk_bf16(lo, hi); }
;     DI void operator()(const f32x4 (&acc)[2][2][4][2], const Unit& u, int wr, int wc, int fr, int fq) const {
;         const int row0 = u.pm * 256 + wr * 64 + fr, col0 = u.pn * 256 + wc * 32 + 8 * fq;
;         const int b = (grow0 + u.pm * 256) >> 11;
;         f32x4 g[2][2], gm[2][2];
; #pragma unroll
;         for (int bj = 0; bj < 2; ++bj) { const int c = col0 + bj * 128; const float* gp = ada + (size_t)b * 6144 + 2048 + c; const float* sp = ada + (size_t)b * 6144 + 4096 + c;
;             g[bj][0] = *(const f32x4*)gp; g[bj][1] = *(const f32x4*)(gp + 4);
;             gm[bj][0] = *(const f32x4*)(g2 + c) * (*(const f32x4*)sp + 1.0f); gm[bj][1] = *(const f32x4*)(g2 + c + 4) * (*(const f32x4*)(sp + 4) + 1.0f); }
; #pragma unroll
;         for (int ai = 0; ai < 2; ++ai)
; #pragma unroll
;             for (int m = 0; m < 4; ++m) { const size_t r = (size_t)(row0 + ai * 128 + m * 16); float ss = 0.f;
; #pragma unroll
;                 for (int bj = 0; bj < 2; ++bj) { const size_t off = r * 1024 + col0 + bj * 128;
;                     f32x4 v0 = *(const f32x4*)(base + off), v1 = *(const f32x4*)(base + off + 4);
;                     v0 += g[bj][0] * acc[ai][bj][m][0]; v1 += g[bj][1] * acc[ai][bj][m][1];
;                     *(f32x4*)(out + off) = v0; *(f32x4*)(out + off + 4) = v1;
;                     ss += (v0[0] * v0[0] + v0[1] * v0[1]) + (v0[2] * v0[2] + v0[3] * v0[3]) + (v1[0] * v1[0] + v1[1] * v1[1]) + (v1[2] * v1[2] + v1[3] * v1[3]);
;                     const f32x4 u0 = v0 * gm[bj][0], u1 = v1 * gm[bj][1];
;                     v4u w; w.x = pk2(u0[0], u0[1]); w.y = pk2(u0[2], u0[3]); w.z = pk2(u1[0], u1[1]); w.w = pk2(u1[2], u1[3]);
;                     *(v4u*)(U2 + off) = w; }
;                 ss += __shfl_xor(ss, 16); ss += __shfl_xor(ss, 32);
	v_pk_add_f32 v[162:163], v[162:163], 1.0 op_sel_hi:[1,0]
	v_pk_add_f32 v[164:165], v[164:165], 1.0 op_sel_hi:[1,0]
	v_pk_add_f32 v[182:183], v[182:183], 1.0 op_sel_hi:[1,0]
	v_pk_add_f32 v[184:185], v[184:185], 1.0 op_sel_hi:[1,0]
	v_pk_add_f32 v[234:235], v[234:235], 1.0 op_sel_hi:[1,0]
	v_pk_add_f32 v[236:237], v[236:237], 1.0 op_sel_hi:[1,0]
	v_pk_add_f32 v[244:245], v[244:245], 1.0 op_sel_hi:[1,0]
	v_pk_add_f32 v[246:247], v[246:247], 1.0 op_sel_hi:[1,0]
	v_pk_mul_f32 v[202:203], v[202:203], v[162:163]
	v_pk_mul_f32 v[204:205], v[204:205], v[164:165]
	v_pk_mul_f32 v[206:207], v[206:207], v[182:183]
	v_pk_mul_f32 v[208:209], v[208:209], v[184:185]
	v_pk_mul_f32 v[210:211], v[210:211], v[234:235]
	v_pk_mul_f32 v[212:213], v[212:213], v[236:237]
	v_pk_mul_f32 v[214:215], v[214:215], v[244:245]
	v_pk_mul_f32 v[216:217], v[216:217], v[246:247]
	s_waitcnt vmcnt(0)
	v_mov_b32_e32 v234, v218
	v_mov_b32_e32 v235, v219
	v_mov_b32_e32 v236, v220
	v_mov_b32_e32 v237, v221
	v_mov_b32_dpp v218, v222 row_shr:8 row_mask:0xf bank_mask:0xc
	v_mov_b32_dpp v219, v223 row_shr:8 row_mask:0xf bank_mask:0xc
	v_mov_b32_dpp v220, v224 row_shr:8 row_mask:0xf bank_mask:0xc
	v_mov_b32_dpp v221, v225 row_shr:8 row_mask:0xf bank_mask:0xc
	v_mov_b32_dpp v222, v234 row_shl:8 row_mask:0xf bank_mask:0x3
	v_mov_b32_dpp v223, v235 row_shl:8 row_mask:0xf bank_mask:0x3
	v_mov_b32_dpp v224, v236 row_shl:8 row_mask:0xf bank_mask:0x3
	v_mov_b32_dpp v225, v237 row_shl:8 row_mask:0xf bank_mask:0x3
	v_mov_b32_e32 v234, v226
	v_mov_b32_e32 v235, v227
	v_mov_b32_e32 v236, v228
	v_mov_b32_e32 v237, v229
	v_mov_b32_dpp v226, v230 row_shr:8 row_mask:0xf bank_mask:0xc
	v_mov_b32_dpp v227, v231 row_shr:8 row_mask:0xf bank_mask:0xc
	v_mov_b32_dpp v228, v232 row_shr:8 row_mask:0xf bank_mask:0xc
	v_mov_b32_dpp v229, v233 row_shr:8 row_mask:0xf bank_mask:0xc
	v_mov_b32_dpp v230, v234 row_shl:8 row_mask:0xf bank_mask:0x3
	v_mov_b32_dpp v231, v235 row_shl:8 row_mask:0xf bank_mask:0x3
	v_mov_b32_dpp v232, v236 row_shl:8 row_mask:0xf bank_mask:0x3
	v_mov_b32_dpp v233, v237 row_shl:8 row_mask:0xf bank_mask:0x3
	v_pk_fma_f32 v[142:143], v[142:143], v[82:83], v[218:219]
	v_pk_fma_f32 v[144:145], v[144:145], v[84:85], v[220:221]
	v_pk_fma_f32 v[138:139], v[138:139], v[86:87], v[222:223]
	v_pk_fma_f32 v[140:141], v[140:141], v[88:89], v[224:225]
	v_pk_fma_f32 v[134:135], v[134:135], v[90:91], v[226:227]
	v_pk_fma_f32 v[136:137], v[136:137], v[92:93], v[228:229]
	v_pk_fma_f32 v[130:131], v[130:131], v[94:95], v[230:231]
	v_pk_fma_f32 v[132:133], v[132:133], v[96:97], v[232:233]
	v_mul_f32_e32 v218, v143, v143
	v_mul_f32_e32 v219, v145, v145
	v_mul_f32_e32 v220, v139, v139
	v_mul_f32_e32 v221, v141, v141
	v_fmac_f32_e32 v218, v142, v142
	v_fmac_f32_e32 v219, v144, v144
	v_fmac_f32_e32 v220, v138, v138
	v_fmac_f32_e32 v221, v140, v140
	v_add_f32_e32 v218, v218, v219
	v_add_f32_e32 v218, v218, v220
	v_add_f32_e32 v218, v221, v218
	v_mul_f32_e32 v222, v135, v135
	v_mul_f32_e32 v223, v137, v137
	v_mul_f32_e32 v224, v131, v131
	v_mul_f32_e32 v225, v133, v133
	v_fmac_f32_e32 v222, v134, v134
	v_fmac_f32_e32 v223, v136, v136
	v_fmac_f32_e32 v224, v130, v130
	v_fmac_f32_e32 v225, v132, v132
	v_add_f32_e32 v222, v222, v223
	v_add_f32_e32 v222, v222, v224
	v_add_f32_e32 v222, v225, v222
	v_add_f32_e32 v248, v218, v222
	ds_bpermute_b32 v201, v180, v248
	v_pk_mul_f32 v[218:219], v[202:203], v[142:143]
	v_pk_mul_f32 v[220:221], v[204:205], v[144:145]
	v_pk_mul_f32 v[222:223], v[206:207], v[138:139]
	v_pk_mul_f32 v[224:225], v[208:209], v[140:141]
	v_pk_mul_f32 v[226:227], v[210:211], v[134:135]
	v_pk_mul_f32 v[228:229], v[212:213], v[136:137]
	v_pk_mul_f32 v[230:231], v[214:215], v[130:131]
	v_pk_mul_f32 v[232:233], v[216:217], v[132:133]
	v_cvt_pk_bf16_f32 v182, v218, v219
	v_cvt_pk_bf16_f32 v183, v220, v221
	v_cvt_pk_bf16_f32 v184, v222, v223
	v_cvt_pk_bf16_f32 v185, v224, v225
	v_cvt_pk_bf16_f32 v244, v226, v227
	v_cvt_pk_bf16_f32 v245, v228, v229
	v_cvt_pk_bf16_f32 v246, v230, v231
	v_cvt_pk_bf16_f32 v247, v232, v233
	s_waitcnt lgkmcnt(0)
	v_add_f32_e32 v248, v248, v201
	ds_bpermute_b32 v201, v181, v248
	v_mov_b32_e32 v234, v244
	v_mov_b32_e32 v235, v245
	v_mov_b32_e32 v236, v246
	v_mov_b32_e32 v237, v247
	v_mov_b32_dpp v244, v182 row_shl:8 row_mask:0xf bank_mask:0x3
	v_mov_b32_dpp v245, v183 row_shl:8 row_mask:0xf bank_mask:0x3
	v_mov_b32_dpp v246, v184 row_shl:8 row_mask:0xf bank_mask:0x3
	v_mov_b32_dpp v247, v185 row_shl:8 row_mask:0xf bank_mask:0x3
	v_mov_b32_dpp v182, v234 row_shr:8 row_mask:0xf bank_mask:0xc
	v_mov_b32_dpp v183, v235 row_shr:8 row_mask:0xf bank_mask:0xc
	v_mov_b32_dpp v184, v236 row_shr:8 row_mask:0xf bank_mask:0xc
	v_mov_b32_dpp v185, v237 row_shr:8 row_mask:0xf bank_mask:0xc
	v_mov_b32_e32 v234, v138
	v_mov_b32_e32 v235, v139
	v_mov_b32_e32 v236, v140
	v_mov_b32_e32 v237, v141
	v_mov_b32_dpp v138, v142 row_shl:8 row_mask:0xf bank_mask:0x3
	v_mov_b32_dpp v139, v143 row_shl:8 row_mask:0xf bank_mask:0x3
	v_mov_b32_dpp v140, v144 row_shl:8 row_mask:0xf bank_mask:0x3
	v_mov_b32_dpp v141, v145 row_shl:8 row_mask:0xf bank_mask:0x3
	v_mov_b32_dpp v142, v234 row_shr:8 row_mask:0xf bank_mask:0xc
	v_mov_b32_dpp v143, v235 row_shr:8 row_mask:0xf bank_mask:0xc
	v_mov_b32_dpp v144, v236 row_shr:8 row_mask:0xf bank_mask:0xc
	v_mov_b32_dpp v145, v237 row_shr:8 row_mask:0xf bank_mask:0xc
	v_mov_b32_e32 v234, v130
	v_mov_b32_e32 v235, v131
	v_mov_b32_e32 v236, v132
	v_mov_b32_e32 v237, v133
	v_mov_b32_dpp v130, v134 row_shl:8 row_mask:0xf bank_mask:0x3
	v_mov_b32_dpp v131, v135 row_shl:8 row_mask:0xf bank_mask:0x3
	v_mov_b32_dpp v132, v136 row_shl:8 row_mask:0xf bank_mask:0x3
	v_mov_b32_dpp v133, v137 row_shl:8 row_mask:0xf bank_mask:0x3
	v_mov_b32_dpp v134, v234 row_shr:8 row_mask:0xf bank_mask:0xc
	v_mov_b32_dpp v135, v235 row_shr:8 row_mask:0xf bank_mask:0xc
	v_mov_b32_dpp v136, v236 row_shr:8 row_mask:0xf bank_mask:0xc
	v_mov_b32_dpp v137, v237 row_shr:8 row_mask:0xf bank_mask:0xc
	s_mov_b64 s[98:99], 0x10000
	v_lshl_add_u64 v[162:163], v[156:157], 0, s[98:99]
	s_mov_b64 s[98:99], 0x18000
	v_lshl_add_u64 v[164:165], v[156:157], 0, s[98:99]
	global_load_dwordx4 v[218:221], v[162:163], off
	global_load_dwordx4 v[222:225], v[164:165], off
	global_load_dwordx4 v[226:229], v[162:163], off offset:128
	global_load_dwordx4 v[230:233], v[164:165], off offset:128
	s_add_u32 s98, s100, 0x0
	s_addc_u32 s99, s101, 0
	v_lshl_add_u64 v[190:191], v[156:157], 0, s[98:99]
	s_add_u32 s98, s100, 0x8000
	s_addc_u32 s99, s101, 0
	v_lshl_add_u64 v[178:179], v[156:157], 0, s[98:99]
	global_store_dwordx4 v[190:191], v[142:145], off
	global_store_dwordx4 v[178:179], v[138:141], off
	global_store_dwordx4 v[190:191], v[134:137], off offset:128
	global_store_dwordx4 v[178:179], v[130:133], off offset:128
	s_mov_b64 s[98:99], 0x0
	v_lshl_add_u64 v[190:191], v[158:159], 0, s[98:99]
	s_mov_b64 s[98:99], 0x4000
	v_lshl_add_u64 v[178:179], v[158:159], 0, s[98:99]
	global_store_dwordx4 v[190:191], v[182:185], off
	global_store_dwordx4 v[178:179], v[244:247], off
	s_waitcnt lgkmcnt(0)
; DI unsigned pk2(float lo, float hi) { return pg8::cvt_pk_bf16(lo, hi); }
;     DI void operator()(const f32x4 (&acc)[2][2][4][2], const Unit& u, int wr, int wc, int fr, int fq) const {
;     ...
;             for (int m = 0; m < 4; ++m) { const size_t r = (size_t)(row0 + ai * 128 + m * 16); float ss = 0.f;
; #pragma unroll
;                 for (int bj = 0; bj < 2; ++bj) { const size_t off = r * 1024 + col0 + bj * 128;
;                     f32x4 v0 = *(const f32x4*)(base + off), v1 = *(const f32x4*)(base + off + 4);
;                     v0 += g[bj][0] * acc[ai][bj][m][0]; v1 += g[bj][1] * acc[ai][bj][m][1];
;                     *(f32x4*)(out + off) = v0; *(f32x4*)(out + off + 4) = v1;
;                     ss += (v0[0] * v0[0] + v0[1] * v0[1]) + (v0[2] * v0[2] + v0[3] * v0[3]) + (v1[0] * v1[0] + v1[1] * v1[1]) + (v1[2] * v1[2] + v1[3] * v1[3]);
;                     const f32x4 u0 = v0 * gm[bj][0], u1 = v1 * gm[bj][1];
;                     v4u w; w.x = pk2(u0[0], u0[1]); w.y = pk2(u0[2], u0[3]); w.z = pk2(u1[0], u1[1]); w.w = pk2(u1[2], u1[3]);
;                     *(v4u*)(U2 + off) = w; }
;                 ss += __shfl_xor(ss, 16); ss += __shfl_xor(ss, 32);
;                 if (fq == 0) atomicAdd(rowss + r, ss); }
	v_add_f32_e32 v248, v248, v201
	s_and_saveexec_b64 s[26:27], s[4:5]
	global_atomic_add_f32 v[160:161], v248, off
	s_or_b64 exec, exec, s[26:27]
	s_waitcnt vmcnt(7)
	v_mov_b32_e32 v234, v218
	v_mov_b32_e32 v235, v219
	v_mov_b32_e32 v236, v220
	v_mov_b32_e32 v237, v221
	v_mov_b32_dpp v218, v222 row_shr:8 row_mask:0xf bank_mask:0xc
	v_mov_b32_dpp v219, v223 row_shr:8 row_mask:0xf bank_mask:0xc
	v_mov_b32_dpp v220, v224 row_shr:8 row_mask:0xf bank_mask:0xc
	v_mov_b32_dpp v221, v225 row_shr:8 row_mask:0xf bank_mask:0xc
	v_mov_b32_dpp v222, v234 row_shl:8 row_mask:0xf bank_mask:0x3
	v_mov_b32_dpp v223, v235 row_shl:8 row_mask:0xf bank_mask:0x3
	v_mov_b32_dpp v224, v236 row_shl:8 row_mask:0xf bank_mask:0x3
	v_mov_b32_dpp v225, v237 row_shl:8 row_mask:0xf bank_mask:0x3
	v_mov_b32_e32 v234, v226
	v_mov_b32_e32 v235, v227
	v_mov_b32_e32 v236, v228
	v_mov_b32_e32 v237, v229
	v_mov_b32_dpp v226, v230 row_shr:8 row_mask:0xf bank_mask:0xc
	v_mov_b32_dpp v227, v231 row_shr:8 row_mask:0xf bank_mask:0xc
	v_mov_b32_dpp v228, v232 row_shr:8 row_mask:0xf bank_mask:0xc
	v_mov_b32_dpp v229, v233 row_shr:8 row_mask:0xf bank_mask:0xc
	v_mov_b32_dpp v230, v234 row_shl:8 row_mask:0xf bank_mask:0x3
	v_mov_b32_dpp v231, v235 row_shl:8 row_mask:0xf bank_mask:0x3
	v_mov_b32_dpp v232, v236 row_shl:8 row_mask:0xf bank_mask:0x3
	v_mov_b32_dpp v233, v237 row_shl:8 row_mask:0xf bank_mask:0x3
	v_pk_fma_f32 v[126:127], v[126:127], v[82:83], v[218:219]
	v_pk_fma_f32 v[128:129], v[128:129], v[84:85], v[220:221]
	v_pk_fma_f32 v[122:123], v[122:123], v[86:87], v[222:223]
	v_pk_fma_f32 v[124:125], v[124:125], v[88:89], v[224:225]
	v_pk_fma_f32 v[118:119], v[118:119], v[90:91], v[226:227]
	v_pk_fma_f32 v[120:121], v[120:121], v[92:93], v[228:229]
	v_pk_fma_f32 v[114:115], v[114:115], v[94:95], v[230:231]
	v_pk_fma_f32 v[116:117], v[116:117], v[96:97], v[232:233]
	v_mul_f32_e32 v218, v127, v127
	v_mul_f32_e32 v219, v129, v129
	v_mul_f32_e32 v220, v123, v123
	v_mul_f32_e32 v221, v125, v125
	v_fmac_f32_e32 v218, v126, v126
	v_fmac_f32_e32 v219, v128, v128
	v_fmac_f32_e32 v220, v122, v122
	v_fmac_f32_e32 v221, v124, v124
	v_add_f32_e32 v218, v218, v219
	v_add_f32_e32 v218, v218, v220
	v_add_f32_e32 v218, v221, v218
	v_mul_f32_e32 v222, v119, v119
	v_mul_f32_e32 v223, v121, v121
	v_mul_f32_e32 v224, v115, v115
	v_mul_f32_e32 v225, v117, v117
	v_fmac_f32_e32 v222, v118, v118
	v_fmac_f32_e32 v223, v120, v120
	v_fmac_f32_e32 v224, v114, v114
	v_fmac_f32_e32 v225, v116, v116
	v_add_f32_e32 v222, v222, v223
	v_add_f32_e32 v222, v222, v224
	v_add_f32_e32 v222, v225, v222
	v_add_f32_e32 v248, v218, v222
	ds_bpermute_b32 v201, v180, v248
	v_pk_mul_f32 v[218:219], v[202:203], v[126:127]
	v_pk_mul_f32 v[220:221], v[204:205], v[128:129]
	v_pk_mul_f32 v[222:223], v[206:207], v[122:123]
	v_pk_mul_f32 v[224:225], v[208:209], v[124:125]
	v_pk_mul_f32 v[226:227], v[210:211], v[118:119]
	v_pk_mul_f32 v[228:229], v[212:213], v[120:121]
	v_pk_mul_f32 v[230:231], v[214:215], v[114:115]
	v_pk_mul_f32 v[232:233], v[216:217], v[116:117]
	v_cvt_pk_bf16_f32 v182, v218, v219
	v_cvt_pk_bf16_f32 v183, v220, v221
	v_cvt_pk_bf16_f32 v184, v222, v223
	v_cvt_pk_bf16_f32 v185, v224, v225
	v_cvt_pk_bf16_f32 v244, v226, v227
	v_cvt_pk_bf16_f32 v245, v228, v229
	v_cvt_pk_bf16_f32 v246, v230, v231
	v_cvt_pk_bf16_f32 v247, v232, v233
	s_waitcnt lgkmcnt(0)
	v_add_f32_e32 v248, v248, v201
	ds_bpermute_b32 v201, v181, v248
	v_mov_b32_e32 v234, v244
	v_mov_b32_e32 v235, v245
	v_mov_b32_e32 v236, v246
	v_mov_b32_e32 v237, v247
	v_mov_b32_dpp v244, v182 row_shl:8 row_mask:0xf bank_mask:0x3
	v_mov_b32_dpp v245, v183 row_shl:8 row_mask:0xf bank_mask:0x3
	v_mov_b32_dpp v246, v184 row_shl:8 row_mask:0xf bank_mask:0x3
	v_mov_b32_dpp v247, v185 row_shl:8 row_mask:0xf bank_mask:0x3
	v_mov_b32_dpp v182, v234 row_shr:8 row_mask:0xf bank_mask:0xc
	v_mov_b32_dpp v183, v235 row_shr:8 row_mask:0xf bank_mask:0xc
	v_mov_b32_dpp v184, v236 row_shr:8 row_mask:0xf bank_mask:0xc
	v_mov_b32_dpp v185, v237 row_shr:8 row_mask:0xf bank_mask:0xc
	v_mov_b32_e32 v234, v122
	v_mov_b32_e32 v235, v123
	v_mov_b32_e32 v236, v124
	v_mov_b32_e32 v237, v125
	v_mov_b32_dpp v122, v126 row_shl:8 row_mask:0xf bank_mask:0x3
	v_mov_b32_dpp v123, v127 row_shl:8 row_mask:0xf bank_mask:0x3
	v_mov_b32_dpp v124, v128 row_shl:8 row_mask:0xf bank_mask:0x3
	v_mov_b32_dpp v125, v129 row_shl:8 row_mask:0xf bank_mask:0x3
	v_mov_b32_dpp v126, v234 row_shr:8 row_mask:0xf bank_mask:0xc
	v_mov_b32_dpp v127, v235 row_shr:8 row_mask:0xf bank_mask:0xc
	v_mov_b32_dpp v128, v236 row_shr:8 row_mask:0xf bank_mask:0xc
	v_mov_b32_dpp v129, v237 row_shr:8 row_mask:0xf bank_mask:0xc
	v_mov_b32_e32 v234, v114
	v_mov_b32_e32 v235, v115
	v_mov_b32_e32 v236, v116
	v_mov_b32_e32 v237, v117
	v_mov_b32_dpp v114, v118 row_shl:8 row_mask:0xf bank_mask:0x3
	v_mov_b32_dpp v115, v119 row_shl:8 row_mask:0xf bank_mask:0x3
	v_mov_b32_dpp v116, v120 row_shl:8 row_mask:0xf bank_mask:0x3
	v_mov_b32_dpp v117, v121 row_shl:8 row_mask:0xf bank_mask:0x3
	v_mov_b32_dpp v118, v234 row_shr:8 row_mask:0xf bank_mask:0xc
	v_mov_b32_dpp v119, v235 row_shr:8 row_mask:0xf bank_mask:0xc
	v_mov_b32_dpp v120, v236 row_shr:8 row_mask:0xf bank_mask:0xc
	v_mov_b32_dpp v121, v237 row_shr:8 row_mask:0xf bank_mask:0xc
	s_mov_b64 s[98:99], 0x20000
	v_lshl_add_u64 v[162:163], v[156:157], 0, s[98:99]
	s_mov_b64 s[98:99], 0x28000
	v_lshl_add_u64 v[164:165], v[156:157], 0, s[98:99]
	global_load_dwordx4 v[218:221], v[162:163], off
	global_load_dwordx4 v[222:225], v[164:165], off
	global_load_dwordx4 v[226:229], v[162:163], off offset:128
	global_load_dwordx4 v[230:233], v[164:165], off offset:128
	s_add_u32 s98, s100, 0x10000
	s_addc_u32 s99, s101, 0
	v_lshl_add_u64 v[190:191], v[156:157], 0, s[98:99]
	s_add_u32 s98, s100, 0x18000
	s_addc_u32 s99, s101, 0
	v_lshl_add_u64 v[178:179], v[156:157], 0, s[98:99]
	global_store_dwordx4 v[190:191], v[126:129], off
	global_store_dwordx4 v[178:179], v[122:125], off
	global_store_dwordx4 v[190:191], v[118:121], off offset:128
	global_store_dwordx4 v[178:179], v[114:117], off offset:128
	s_mov_b64 s[98:99], 0x8000
	v_lshl_add_u64 v[190:191], v[158:159], 0, s[98:99]
	s_mov_b64 s[98:99], 0xc000
	v_lshl_add_u64 v[178:179], v[158:159], 0, s[98:99]
	global_store_dwordx4 v[190:191], v[182:185], off
	global_store_dwordx4 v[178:179], v[244:247], off
	s_waitcnt lgkmcnt(0)
; DI unsigned pk2(float lo, float hi) { return pg8::cvt_pk_bf16(lo, hi); }
;     DI void operator()(const f32x4 (&acc)[2][2][4][2], const Unit& u, int wr, int wc, int fr, int fq) const {
;     ...
;             for (int m = 0; m < 4; ++m) { const size_t r = (size_t)(row0 + ai * 128 + m * 16); float ss = 0.f;
; #pragma unroll
;                 for (int bj = 0; bj < 2; ++bj) { const size_t off = r * 1024 + col0 + bj * 128;
;                     f32x4 v0 = *(const f32x4*)(base + off), v1 = *(const f32x4*)(base + off + 4);
;                     v0 += g[bj][0] * acc[ai][bj][m][0]; v1 += g[bj][1] * acc[ai][bj][m][1];
;                     *(f32x4*)(out + off) = v0; *(f32x4*)(out + off + 4) = v1;
;                     ss += (v0[0] * v0[0] + v0[1] * v0[1]) + (v0[2] * v0[2] + v0[3] * v0[3]) + (v1[0] * v1[0] + v1[1] * v1[1]) + (v1[2] * v1[2] + v1[3] * v1[3]);
;                     const f32x4 u0 = v0 * gm[bj][0], u1 = v1 * gm[bj][1];
;                     v4u w; w.x = pk2(u0[0], u0[1]); w.y = pk2(u0[2], u0[3]); w.z = pk2(u1[0], u1[1]); w.w = pk2(u1[2], u1[3]);
;                     *(v4u*)(U2 + off) = w; }
;                 ss += __shfl_xor(ss, 16); ss += __shfl_xor(ss, 32);
;                 if (fq == 0) atomicAdd(rowss + r, ss); }
	v_add_f32_e32 v248, v248, v201
	s_and_saveexec_b64 s[26:27], s[4:5]
	global_atomic_add_f32 v[160:161], v248, off offset:64
	s_or_b64 exec, exec, s[26:27]
	s_waitcnt vmcnt(7)
	v_mov_b32_e32 v234, v218
	v_mov_b32_e32 v235, v219
	v_mov_b32_e32 v236, v220
	v_mov_b32_e32 v237, v221
	v_mov_b32_dpp v218, v222 row_shr:8 row_mask:0xf bank_mask:0xc
	v_mov_b32_dpp v219, v223 row_shr:8 row_mask:0xf bank_mask:0xc
	v_mov_b32_dpp v220, v224 row_shr:8 row_mask:0xf bank_mask:0xc
	v_mov_b32_dpp v221, v225 row_shr:8 row_mask:0xf bank_mask:0xc
	v_mov_b32_dpp v222, v234 row_shl:8 row_mask:0xf bank_mask:0x3
	v_mov_b32_dpp v223, v235 row_shl:8 row_mask:0xf bank_mask:0x3
	v_mov_b32_dpp v224, v236 row_shl:8 row_mask:0xf bank_mask:0x3
	v_mov_b32_dpp v225, v237 row_shl:8 row_mask:0xf bank_mask:0x3
	v_mov_b32_e32 v234, v226
	v_mov_b32_e32 v235, v227
	v_mov_b32_e32 v236, v228
	v_mov_b32_e32 v237, v229
	v_mov_b32_dpp v226, v230 row_shr:8 row_mask:0xf bank_mask:0xc
	v_mov_b32_dpp v227, v231 row_shr:8 row_mask:0xf bank_mask:0xc
	v_mov_b32_dpp v228, v232 row_shr:8 row_mask:0xf bank_mask:0xc
	v_mov_b32_dpp v229, v233 row_shr:8 row_mask:0xf bank_mask:0xc
	v_mov_b32_dpp v230, v234 row_shl:8 row_mask:0xf bank_mask:0x3
	v_mov_b32_dpp v231, v235 row_shl:8 row_mask:0xf bank_mask:0x3
	v_mov_b32_dpp v232, v236 row_shl:8 row_mask:0xf bank_mask:0x3
	v_mov_b32_dpp v233, v237 row_shl:8 row_mask:0xf bank_mask:0x3
	v_pk_fma_f32 v[110:111], v[110:111], v[82:83], v[218:219]
	v_pk_fma_f32 v[112:113], v[112:113], v[84:85], v[220:221]
	v_pk_fma_f32 v[106:107], v[106:107], v[86:87], v[222:223]
	v_pk_fma_f32 v[108:109], v[108:109], v[88:89], v[224:225]
	v_pk_fma_f32 v[102:103], v[102:103], v[90:91], v[226:227]
	v_pk_fma_f32 v[104:105], v[104:105], v[92:93], v[228:229]
	v_pk_fma_f32 v[98:99], v[98:99], v[94:95], v[230:231]
	v_pk_fma_f32 v[100:101], v[100:101], v[96:97], v[232:233]
	v_mul_f32_e32 v218, v111, v111
	v_mul_f32_e32 v219, v113, v113
	v_mul_f32_e32 v220, v107, v107
	v_mul_f32_e32 v221, v109, v109
	v_fmac_f32_e32 v218, v110, v110
	v_fmac_f32_e32 v219, v112, v112
	v_fmac_f32_e32 v220, v106, v106
	v_fmac_f32_e32 v221, v108, v108
	v_add_f32_e32 v218, v218, v219
	v_add_f32_e32 v218, v218, v220
	v_add_f32_e32 v218, v221, v218
	v_mul_f32_e32 v222, v103, v103
	v_mul_f32_e32 v223, v105, v105
	v_mul_f32_e32 v224, v99, v99
	v_mul_f32_e32 v225, v101, v101
	v_fmac_f32_e32 v222, v102, v102
	v_fmac_f32_e32 v223, v104, v104
	v_fmac_f32_e32 v224, v98, v98
	v_fmac_f32_e32 v225, v100, v100
	v_add_f32_e32 v222, v222, v223
	v_add_f32_e32 v222, v222, v224
	v_add_f32_e32 v222, v225, v222
	v_add_f32_e32 v248, v218, v222
	ds_bpermute_b32 v201, v180, v248
	v_pk_mul_f32 v[218:219], v[202:203], v[110:111]
	v_pk_mul_f32 v[220:221], v[204:205], v[112:113]
	v_pk_mul_f32 v[222:223], v[206:207], v[106:107]
	v_pk_mul_f32 v[224:225], v[208:209], v[108:109]
	v_pk_mul_f32 v[226:227], v[210:211], v[102:103]
	v_pk_mul_f32 v[228:229], v[212:213], v[104:105]
	v_pk_mul_f32 v[230:231], v[214:215], v[98:99]
	v_pk_mul_f32 v[232:233], v[216:217], v[100:101]
	v_cvt_pk_bf16_f32 v182, v218, v219
	v_cvt_pk_bf16_f32 v183, v220, v221
	v_cvt_pk_bf16_f32 v184, v222, v223
	v_cvt_pk_bf16_f32 v185, v224, v225
	v_cvt_pk_bf16_f32 v244, v226, v227
	v_cvt_pk_bf16_f32 v245, v228, v229
	v_cvt_pk_bf16_f32 v246, v230, v231
	v_cvt_pk_bf16_f32 v247, v232, v233
	s_waitcnt lgkmcnt(0)
	v_add_f32_e32 v248, v248, v201
	ds_bpermute_b32 v201, v181, v248
	v_mov_b32_e32 v234, v244
	v_mov_b32_e32 v235, v245
	v_mov_b32_e32 v236, v246
	v_mov_b32_e32 v237, v247
	v_mov_b32_dpp v244, v182 row_shl:8 row_mask:0xf bank_mask:0x3
	v_mov_b32_dpp v245, v183 row_shl:8 row_mask:0xf bank_mask:0x3
	v_mov_b32_dpp v246, v184 row_shl:8 row_mask:0xf bank_mask:0x3
	v_mov_b32_dpp v247, v185 row_shl:8 row_mask:0xf bank_mask:0x3
	v_mov_b32_dpp v182, v234 row_shr:8 row_mask:0xf bank_mask:0xc
	v_mov_b32_dpp v183, v235 row_shr:8 row_mask:0xf bank_mask:0xc
	v_mov_b32_dpp v184, v236 row_shr:8 row_mask:0xf bank_mask:0xc
	v_mov_b32_dpp v185, v237 row_shr:8 row_mask:0xf bank_mask:0xc
	v_mov_b32_e32 v234, v106
	v_mov_b32_e32 v235, v107
	v_mov_b32_e32 v236, v108
	v_mov_b32_e32 v237, v109
	v_mov_b32_dpp v106, v110 row_shl:8 row_mask:0xf bank_mask:0x3
	v_mov_b32_dpp v107, v111 row_shl:8 row_mask:0xf bank_mask:0x3
	v_mov_b32_dpp v108, v112 row_shl:8 row_mask:0xf bank_mask:0x3
	v_mov_b32_dpp v109, v113 row_shl:8 row_mask:0xf bank_mask:0x3
	v_mov_b32_dpp v110, v234 row_shr:8 row_mask:0xf bank_mask:0xc
	v_mov_b32_dpp v111, v235 row_shr:8 row_mask:0xf bank_mask:0xc
	v_mov_b32_dpp v112, v236 row_shr:8 row_mask:0xf bank_mask:0xc
	v_mov_b32_dpp v113, v237 row_shr:8 row_mask:0xf bank_mask:0xc
	v_mov_b32_e32 v234, v98
	v_mov_b32_e32 v235, v99
	v_mov_b32_e32 v236, v100
	v_mov_b32_e32 v237, v101
	v_mov_b32_dpp v98, v102 row_shl:8 row_mask:0xf bank_mask:0x3
	v_mov_b32_dpp v99, v103 row_shl:8 row_mask:0xf bank_mask:0x3
	v_mov_b32_dpp v100, v104 row_shl:8 row_mask:0xf bank_mask:0x3
	v_mov_b32_dpp v101, v105 row_shl:8 row_mask:0xf bank_mask:0x3
	v_mov_b32_dpp v102, v234 row_shr:8 row_mask:0xf bank_mask:0xc
	v_mov_b32_dpp v103, v235 row_shr:8 row_mask:0xf bank_mask:0xc
	v_mov_b32_dpp v104, v236 row_shr:8 row_mask:0xf bank_mask:0xc
	v_mov_b32_dpp v105, v237 row_shr:8 row_mask:0xf bank_mask:0xc
	s_mov_b64 s[98:99], 0x30000
	v_lshl_add_u64 v[162:163], v[156:157], 0, s[98:99]
	s_mov_b64 s[98:99], 0x38000
	v_lshl_add_u64 v[164:165], v[156:157], 0, s[98:99]
	global_load_dwordx4 v[218:221], v[162:163], off
	global_load_dwordx4 v[222:225], v[164:165], off
	global_load_dwordx4 v[226:229], v[162:163], off offset:128
	global_load_dwordx4 v[230:233], v[164:165], off offset:128
	s_add_u32 s98, s100, 0x20000
	s_addc_u32 s99, s101, 0
	v_lshl_add_u64 v[190:191], v[156:157], 0, s[98:99]
	s_add_u32 s98, s100, 0x28000
	s_addc_u32 s99, s101, 0
	v_lshl_add_u64 v[178:179], v[156:157], 0, s[98:99]
	global_store_dwordx4 v[190:191], v[110:113], off
	global_store_dwordx4 v[178:179], v[106:109], off
	global_store_dwordx4 v[190:191], v[102:105], off offset:128
	global_store_dwordx4 v[178:179], v[98:101], off offset:128
	s_mov_b64 s[98:99], 0x10000
	v_lshl_add_u64 v[190:191], v[158:159], 0, s[98:99]
	s_mov_b64 s[98:99], 0x14000
	v_lshl_add_u64 v[178:179], v[158:159], 0, s[98:99]
	global_store_dwordx4 v[190:191], v[182:185], off
	global_store_dwordx4 v[178:179], v[244:247], off
	s_waitcnt lgkmcnt(0)
; DI unsigned pk2(float lo, float hi) { return pg8::cvt_pk_bf16(lo, hi); }
;     DI void operator()(const f32x4 (&acc)[2][2][4][2], const Unit& u, int wr, int wc, int fr, int fq) const {
;     ...
;             for (int m = 0; m < 4; ++m) { const size_t r = (size_t)(row0 + ai * 128 + m * 16); float ss = 0.f;
; #pragma unroll
;                 for (int bj = 0; bj < 2; ++bj) { const size_t off = r * 1024 + col0 + bj * 128;
;                     f32x4 v0 = *(const f32x4*)(base + off), v1 = *(const f32x4*)(base + off + 4);
;                     v0 += g[bj][0] * acc[ai][bj][m][0]; v1 += g[bj][1] * acc[ai][bj][m][1];
;                     *(f32x4*)(out + off) = v0; *(f32x4*)(out + off + 4) = v1;
;                     ss += (v0[0] * v0[0] + v0[1] * v0[1]) + (v0[2] * v0[2] + v0[3] * v0[3]) + (v1[0] * v1[0] + v1[1] * v1[1]) + (v1[2] * v1[2] + v1[3] * v1[3]);
;                     const f32x4 u0 = v0 * gm[bj][0], u1 = v1 * gm[bj][1];
;                     v4u w; w.x = pk2(u0[0], u0[1]); w.y = pk2(u0[2], u0[3]); w.z = pk2(u1[0], u1[1]); w.w = pk2(u1[2], u1[3]);
;                     *(v4u*)(U2 + off) = w; }
;                 ss += __shfl_xor(ss, 16); ss += __shfl_xor(ss, 32);
;                 if (fq == 0) atomicAdd(rowss + r, ss); }
	v_add_f32_e32 v248, v248, v201
	s_and_saveexec_b64 s[26:27], s[4:5]
	global_atomic_add_f32 v[160:161], v248, off offset:128
	s_or_b64 exec, exec, s[26:27]
	s_waitcnt vmcnt(7)
	v_mov_b32_e32 v234, v218
	v_mov_b32_e32 v235, v219
	v_mov_b32_e32 v236, v220
	v_mov_b32_e32 v237, v221
	v_mov_b32_dpp v218, v222 row_shr:8 row_mask:0xf bank_mask:0xc
	v_mov_b32_dpp v219, v223 row_shr:8 row_mask:0xf bank_mask:0xc
	v_mov_b32_dpp v220, v224 row_shr:8 row_mask:0xf bank_mask:0xc
	v_mov_b32_dpp v221, v225 row_shr:8 row_mask:0xf bank_mask:0xc
	v_mov_b32_dpp v222, v234 row_shl:8 row_mask:0xf bank_mask:0x3
	v_mov_b32_dpp v223, v235 row_shl:8 row_mask:0xf bank_mask:0x3
	v_mov_b32_dpp v224, v236 row_shl:8 row_mask:0xf bank_mask:0x3
	v_mov_b32_dpp v225, v237 row_shl:8 row_mask:0xf bank_mask:0x3
	v_mov_b32_e32 v234, v226
	v_mov_b32_e32 v235, v227
	v_mov_b32_e32 v236, v228
	v_mov_b32_e32 v237, v229
	v_mov_b32_dpp v226, v230 row_shr:8 row_mask:0xf bank_mask:0xc
	v_mov_b32_dpp v227, v231 row_shr:8 row_mask:0xf bank_mask:0xc
	v_mov_b32_dpp v228, v232 row_shr:8 row_mask:0xf bank_mask:0xc
	v_mov_b32_dpp v229, v233 row_shr:8 row_mask:0xf bank_mask:0xc
	v_mov_b32_dpp v230, v234 row_shl:8 row_mask:0xf bank_mask:0x3
	v_mov_b32_dpp v231, v235 row_shl:8 row_mask:0xf bank_mask:0x3
	v_mov_b32_dpp v232, v236 row_shl:8 row_mask:0xf bank_mask:0x3
	v_mov_b32_dpp v233, v237 row_shl:8 row_mask:0xf bank_mask:0x3
	v_pk_fma_f32 v[78:79], v[78:79], v[82:83], v[218:219]
	v_pk_fma_f32 v[80:81], v[80:81], v[84:85], v[220:221]
	v_pk_fma_f32 v[74:75], v[74:75], v[86:87], v[222:223]
	v_pk_fma_f32 v[76:77], v[76:77], v[88:89], v[224:225]
	v_pk_fma_f32 v[70:71], v[70:71], v[90:91], v[226:227]
	v_pk_fma_f32 v[72:73], v[72:73], v[92:93], v[228:229]
	v_pk_fma_f32 v[66:67], v[66:67], v[94:95], v[230:231]
	v_pk_fma_f32 v[68:69], v[68:69], v[96:97], v[232:233]
	v_mul_f32_e32 v218, v79, v79
	v_mul_f32_e32 v219, v81, v81
	v_mul_f32_e32 v220, v75, v75
	v_mul_f32_e32 v221, v77, v77
	v_fmac_f32_e32 v218, v78, v78
	v_fmac_f32_e32 v219, v80, v80
	v_fmac_f32_e32 v220, v74, v74
	v_fmac_f32_e32 v221, v76, v76
	v_add_f32_e32 v218, v218, v219
	v_add_f32_e32 v218, v218, v220
	v_add_f32_e32 v218, v221, v218
	v_mul_f32_e32 v222, v71, v71
	v_mul_f32_e32 v223, v73, v73
	v_mul_f32_e32 v224, v67, v67
	v_mul_f32_e32 v225, v69, v69
	v_fmac_f32_e32 v222, v70, v70
	v_fmac_f32_e32 v223, v72, v72
	v_fmac_f32_e32 v224, v66, v66
	v_fmac_f32_e32 v225, v68, v68
	v_add_f32_e32 v222, v222, v223
	v_add_f32_e32 v222, v222, v224
	v_add_f32_e32 v222, v225, v222
	v_add_f32_e32 v248, v218, v222
	ds_bpermute_b32 v201, v180, v248
	v_pk_mul_f32 v[218:219], v[202:203], v[78:79]
	v_pk_mul_f32 v[220:221], v[204:205], v[80:81]
	v_pk_mul_f32 v[222:223], v[206:207], v[74:75]
	v_pk_mul_f32 v[224:225], v[208:209], v[76:77]
	v_pk_mul_f32 v[226:227], v[210:211], v[70:71]
	v_pk_mul_f32 v[228:229], v[212:213], v[72:73]
	v_pk_mul_f32 v[230:231], v[214:215], v[66:67]
	v_pk_mul_f32 v[232:233], v[216:217], v[68:69]
	v_cvt_pk_bf16_f32 v182, v218, v219
	v_cvt_pk_bf16_f32 v183, v220, v221
	v_cvt_pk_bf16_f32 v184, v222, v223
	v_cvt_pk_bf16_f32 v185, v224, v225
	v_cvt_pk_bf16_f32 v244, v226, v227
	v_cvt_pk_bf16_f32 v245, v228, v229
	v_cvt_pk_bf16_f32 v246, v230, v231
	v_cvt_pk_bf16_f32 v247, v232, v233
	s_waitcnt lgkmcnt(0)
	v_add_f32_e32 v248, v248, v201
	ds_bpermute_b32 v201, v181, v248
	v_mov_b32_e32 v234, v244
	v_mov_b32_e32 v235, v245
	v_mov_b32_e32 v236, v246
	v_mov_b32_e32 v237, v247
	v_mov_b32_dpp v244, v182 row_shl:8 row_mask:0xf bank_mask:0x3
	v_mov_b32_dpp v245, v183 row_shl:8 row_mask:0xf bank_mask:0x3
	v_mov_b32_dpp v246, v184 row_shl:8 row_mask:0xf bank_mask:0x3
	v_mov_b32_dpp v247, v185 row_shl:8 row_mask:0xf bank_mask:0x3
	v_mov_b32_dpp v182, v234 row_shr:8 row_mask:0xf bank_mask:0xc
	v_mov_b32_dpp v183, v235 row_shr:8 row_mask:0xf bank_mask:0xc
	v_mov_b32_dpp v184, v236 row_shr:8 row_mask:0xf bank_mask:0xc
	v_mov_b32_dpp v185, v237 row_shr:8 row_mask:0xf bank_mask:0xc
	v_mov_b32_e32 v234, v74
	v_mov_b32_e32 v235, v75
	v_mov_b32_e32 v236, v76
	v_mov_b32_e32 v237, v77
	v_mov_b32_dpp v74, v78 row_shl:8 row_mask:0xf bank_mask:0x3
	v_mov_b32_dpp v75, v79 row_shl:8 row_mask:0xf bank_mask:0x3
	v_mov_b32_dpp v76, v80 row_shl:8 row_mask:0xf bank_mask:0x3
	v_mov_b32_dpp v77, v81 row_shl:8 row_mask:0xf bank_mask:0x3
	v_mov_b32_dpp v78, v234 row_shr:8 row_mask:0xf bank_mask:0xc
	v_mov_b32_dpp v79, v235 row_shr:8 row_mask:0xf bank_mask:0xc
	v_mov_b32_dpp v80, v236 row_shr:8 row_mask:0xf bank_mask:0xc
	v_mov_b32_dpp v81, v237 row_shr:8 row_mask:0xf bank_mask:0xc
	v_mov_b32_e32 v234, v66
	v_mov_b32_e32 v235, v67
	v_mov_b32_e32 v236, v68
	v_mov_b32_e32 v237, v69
	v_mov_b32_dpp v66, v70 row_shl:8 row_mask:0xf bank_mask:0x3
	v_mov_b32_dpp v67, v71 row_shl:8 row_mask:0xf bank_mask:0x3
	v_mov_b32_dpp v68, v72 row_shl:8 row_mask:0xf bank_mask:0x3
	v_mov_b32_dpp v69, v73 row_shl:8 row_mask:0xf bank_mask:0x3
	v_mov_b32_dpp v70, v234 row_shr:8 row_mask:0xf bank_mask:0xc
	v_mov_b32_dpp v71, v235 row_shr:8 row_mask:0xf bank_mask:0xc
	v_mov_b32_dpp v72, v236 row_shr:8 row_mask:0xf bank_mask:0xc
	v_mov_b32_dpp v73, v237 row_shr:8 row_mask:0xf bank_mask:0xc
	s_mov_b64 s[98:99], 0x80000
	v_lshl_add_u64 v[162:163], v[156:157], 0, s[98:99]
	s_mov_b64 s[98:99], 0x88000
	v_lshl_add_u64 v[164:165], v[156:157], 0, s[98:99]
	global_load_dwordx4 v[218:221], v[162:163], off
	global_load_dwordx4 v[222:225], v[164:165], off
	global_load_dwordx4 v[226:229], v[162:163], off offset:128
	global_load_dwordx4 v[230:233], v[164:165], off offset:128
	s_add_u32 s98, s100, 0x30000
	s_addc_u32 s99, s101, 0
	v_lshl_add_u64 v[190:191], v[156:157], 0, s[98:99]
	s_add_u32 s98, s100, 0x38000
	s_addc_u32 s99, s101, 0
	v_lshl_add_u64 v[178:179], v[156:157], 0, s[98:99]
	global_store_dwordx4 v[190:191], v[78:81], off
	global_store_dwordx4 v[178:179], v[74:77], off
	global_store_dwordx4 v[190:191], v[70:73], off offset:128
	global_store_dwordx4 v[178:179], v[66:69], off offset:128
	s_mov_b64 s[98:99], 0x18000
	v_lshl_add_u64 v[190:191], v[158:159], 0, s[98:99]
	s_mov_b64 s[98:99], 0x1c000
	v_lshl_add_u64 v[178:179], v[158:159], 0, s[98:99]
	global_store_dwordx4 v[190:191], v[182:185], off
	global_store_dwordx4 v[178:179], v[244:247], off
	s_waitcnt lgkmcnt(0)
; DI unsigned pk2(float lo, float hi) { return pg8::cvt_pk_bf16(lo, hi); }
;     DI void operator()(const f32x4 (&acc)[2][2][4][2], const Unit& u, int wr, int wc, int fr, int fq) const {
;     ...
;             for (int m = 0; m < 4; ++m) { const size_t r = (size_t)(row0 + ai * 128 + m * 16); float ss = 0.f;
; #pragma unroll
;                 for (int bj = 0; bj < 2; ++bj) { const size_t off = r * 1024 + col0 + bj * 128;
;                     f32x4 v0 = *(const f32x4*)(base + off), v1 = *(const f32x4*)(base + off + 4);
;                     v0 += g[bj][0] * acc[ai][bj][m][0]; v1 += g[bj][1] * acc[ai][bj][m][1];
;                     *(f32x4*)(out + off) = v0; *(f32x4*)(out + off + 4) = v1;
;                     ss += (v0[0] * v0[0] + v0[1] * v0[1]) + (v0[2] * v0[2] + v0[3] * v0[3]) + (v1[0] * v1[0] + v1[1] * v1[1]) + (v1[2] * v1[2] + v1[3] * v1[3]);
;                     const f32x4 u0 = v0 * gm[bj][0], u1 = v1 * gm[bj][1];
;                     v4u w; w.x = pk2(u0[0], u0[1]); w.y = pk2(u0[2], u0[3]); w.z = pk2(u1[0], u1[1]); w.w = pk2(u1[2], u1[3]);
;                     *(v4u*)(U2 + off) = w; }
;                 ss += __shfl_xor(ss, 16); ss += __shfl_xor(ss, 32);
;                 if (fq == 0) atomicAdd(rowss + r, ss); }
	v_add_f32_e32 v248, v248, v201
	s_and_saveexec_b64 s[26:27], s[4:5]
	global_atomic_add_f32 v[160:161], v248, off offset:192
	s_or_b64 exec, exec, s[26:27]
	s_waitcnt vmcnt(7)
	v_mov_b32_e32 v234, v218
	v_mov_b32_e32 v235, v219
	v_mov_b32_e32 v236, v220
	v_mov_b32_e32 v237, v221
	v_mov_b32_dpp v218, v222 row_shr:8 row_mask:0xf bank_mask:0xc
	v_mov_b32_dpp v219, v223 row_shr:8 row_mask:0xf bank_mask:0xc
	v_mov_b32_dpp v220, v224 row_shr:8 row_mask:0xf bank_mask:0xc
	v_mov_b32_dpp v221, v225 row_shr:8 row_mask:0xf bank_mask:0xc
	v_mov_b32_dpp v222, v234 row_shl:8 row_mask:0xf bank_mask:0x3
	v_mov_b32_dpp v223, v235 row_shl:8 row_mask:0xf bank_mask:0x3
	v_mov_b32_dpp v224, v236 row_shl:8 row_mask:0xf bank_mask:0x3
	v_mov_b32_dpp v225, v237 row_shl:8 row_mask:0xf bank_mask:0x3
	v_mov_b32_e32 v234, v226
	v_mov_b32_e32 v235, v227
	v_mov_b32_e32 v236, v228
	v_mov_b32_e32 v237, v229
	v_mov_b32_dpp v226, v230 row_shr:8 row_mask:0xf bank_mask:0xc
	v_mov_b32_dpp v227, v231 row_shr:8 row_mask:0xf bank_mask:0xc
	v_mov_b32_dpp v228, v232 row_shr:8 row_mask:0xf bank_mask:0xc
	v_mov_b32_dpp v229, v233 row_shr:8 row_mask:0xf bank_mask:0xc
	v_mov_b32_dpp v230, v234 row_shl:8 row_mask:0xf bank_mask:0x3
	v_mov_b32_dpp v231, v235 row_shl:8 row_mask:0xf bank_mask:0x3
	v_mov_b32_dpp v232, v236 row_shl:8 row_mask:0xf bank_mask:0x3
	v_mov_b32_dpp v233, v237 row_shl:8 row_mask:0xf bank_mask:0x3
	v_pk_fma_f32 v[62:63], v[62:63], v[82:83], v[218:219]
	v_pk_fma_f32 v[64:65], v[64:65], v[84:85], v[220:221]
	v_pk_fma_f32 v[58:59], v[58:59], v[86:87], v[222:223]
	v_pk_fma_f32 v[60:61], v[60:61], v[88:89], v[224:225]
	v_pk_fma_f32 v[54:55], v[54:55], v[90:91], v[226:227]
	v_pk_fma_f32 v[56:57], v[56:57], v[92:93], v[228:229]
	v_pk_fma_f32 v[50:51], v[50:51], v[94:95], v[230:231]
	v_pk_fma_f32 v[52:53], v[52:53], v[96:97], v[232:233]
	v_mul_f32_e32 v218, v63, v63
	v_mul_f32_e32 v219, v65, v65
	v_mul_f32_e32 v220, v59, v59
	v_mul_f32_e32 v221, v61, v61
	v_fmac_f32_e32 v218, v62, v62
	v_fmac_f32_e32 v219, v64, v64
	v_fmac_f32_e32 v220, v58, v58
	v_fmac_f32_e32 v221, v60, v60
	v_add_f32_e32 v218, v218, v219
	v_add_f32_e32 v218, v218, v220
	v_add_f32_e32 v218, v221, v218
	v_mul_f32_e32 v222, v55, v55
	v_mul_f32_e32 v223, v57, v57
	v_mul_f32_e32 v224, v51, v51
	v_mul_f32_e32 v225, v53, v53
	v_fmac_f32_e32 v222, v54, v54
	v_fmac_f32_e32 v223, v56, v56
	v_fmac_f32_e32 v224, v50, v50
	v_fmac_f32_e32 v225, v52, v52
	v_add_f32_e32 v222, v222, v223
	v_add_f32_e32 v222, v222, v224
	v_add_f32_e32 v222, v225, v222
	v_add_f32_e32 v248, v218, v222
	ds_bpermute_b32 v201, v180, v248
	v_pk_mul_f32 v[218:219], v[202:203], v[62:63]
	v_pk_mul_f32 v[220:221], v[204:205], v[64:65]
	v_pk_mul_f32 v[222:223], v[206:207], v[58:59]
	v_pk_mul_f32 v[224:225], v[208:209], v[60:61]
	v_pk_mul_f32 v[226:227], v[210:211], v[54:55]
	v_pk_mul_f32 v[228:229], v[212:213], v[56:57]
	v_pk_mul_f32 v[230:231], v[214:215], v[50:51]
	v_pk_mul_f32 v[232:233], v[216:217], v[52:53]
	v_cvt_pk_bf16_f32 v182, v218, v219
	v_cvt_pk_bf16_f32 v183, v220, v221
	v_cvt_pk_bf16_f32 v184, v222, v223
	v_cvt_pk_bf16_f32 v185, v224, v225
	v_cvt_pk_bf16_f32 v244, v226, v227
	v_cvt_pk_bf16_f32 v245, v228, v229
	v_cvt_pk_bf16_f32 v246, v230, v231
	v_cvt_pk_bf16_f32 v247, v232, v233
	s_waitcnt lgkmcnt(0)
	v_add_f32_e32 v248, v248, v201
	ds_bpermute_b32 v201, v181, v248
	v_mov_b32_e32 v234, v244
	v_mov_b32_e32 v235, v245
	v_mov_b32_e32 v236, v246
	v_mov_b32_e32 v237, v247
	v_mov_b32_dpp v244, v182 row_shl:8 row_mask:0xf bank_mask:0x3
	v_mov_b32_dpp v245, v183 row_shl:8 row_mask:0xf bank_mask:0x3
	v_mov_b32_dpp v246, v184 row_shl:8 row_mask:0xf bank_mask:0x3
	v_mov_b32_dpp v247, v185 row_shl:8 row_mask:0xf bank_mask:0x3
	v_mov_b32_dpp v182, v234 row_shr:8 row_mask:0xf bank_mask:0xc
	v_mov_b32_dpp v183, v235 row_shr:8 row_mask:0xf bank_mask:0xc
	v_mov_b32_dpp v184, v236 row_shr:8 row_mask:0xf bank_mask:0xc
	v_mov_b32_dpp v185, v237 row_shr:8 row_mask:0xf bank_mask:0xc
	v_mov_b32_e32 v234, v58
	v_mov_b32_e32 v235, v59
	v_mov_b32_e32 v236, v60
	v_mov_b32_e32 v237, v61
	v_mov_b32_dpp v58, v62 row_shl:8 row_mask:0xf bank_mask:0x3
	v_mov_b32_dpp v59, v63 row_shl:8 row_mask:0xf bank_mask:0x3
	v_mov_b32_dpp v60, v64 row_shl:8 row_mask:0xf bank_mask:0x3
	v_mov_b32_dpp v61, v65 row_shl:8 row_mask:0xf bank_mask:0x3
	v_mov_b32_dpp v62, v234 row_shr:8 row_mask:0xf bank_mask:0xc
	v_mov_b32_dpp v63, v235 row_shr:8 row_mask:0xf bank_mask:0xc
	v_mov_b32_dpp v64, v236 row_shr:8 row_mask:0xf bank_mask:0xc
	v_mov_b32_dpp v65, v237 row_shr:8 row_mask:0xf bank_mask:0xc
	v_mov_b32_e32 v234, v50
	v_mov_b32_e32 v235, v51
	v_mov_b32_e32 v236, v52
	v_mov_b32_e32 v237, v53
	v_mov_b32_dpp v50, v54 row_shl:8 row_mask:0xf bank_mask:0x3
	v_mov_b32_dpp v51, v55 row_shl:8 row_mask:0xf bank_mask:0x3
	v_mov_b32_dpp v52, v56 row_shl:8 row_mask:0xf bank_mask:0x3
	v_mov_b32_dpp v53, v57 row_shl:8 row_mask:0xf bank_mask:0x3
	v_mov_b32_dpp v54, v234 row_shr:8 row_mask:0xf bank_mask:0xc
	v_mov_b32_dpp v55, v235 row_shr:8 row_mask:0xf bank_mask:0xc
	v_mov_b32_dpp v56, v236 row_shr:8 row_mask:0xf bank_mask:0xc
	v_mov_b32_dpp v57, v237 row_shr:8 row_mask:0xf bank_mask:0xc
	s_mov_b64 s[98:99], 0x90000
	v_lshl_add_u64 v[162:163], v[156:157], 0, s[98:99]
	s_mov_b64 s[98:99], 0x98000
	v_lshl_add_u64 v[164:165], v[156:157], 0, s[98:99]
	global_load_dwordx4 v[218:221], v[162:163], off
	global_load_dwordx4 v[222:225], v[164:165], off
	global_load_dwordx4 v[226:229], v[162:163], off offset:128
	global_load_dwordx4 v[230:233], v[164:165], off offset:128
	s_add_u32 s98, s100, 0x80000
	s_addc_u32 s99, s101, 0
	v_lshl_add_u64 v[190:191], v[156:157], 0, s[98:99]
	s_add_u32 s98, s100, 0x88000
	s_addc_u32 s99, s101, 0
	v_lshl_add_u64 v[178:179], v[156:157], 0, s[98:99]
	global_store_dwordx4 v[190:191], v[62:65], off
	global_store_dwordx4 v[178:179], v[58:61], off
	global_store_dwordx4 v[190:191], v[54:57], off offset:128
	global_store_dwordx4 v[178:179], v[50:53], off offset:128
	s_mov_b64 s[98:99], 0x40000
	v_lshl_add_u64 v[190:191], v[158:159], 0, s[98:99]
	s_mov_b64 s[98:99], 0x44000
	v_lshl_add_u64 v[178:179], v[158:159], 0, s[98:99]
	global_store_dwordx4 v[190:191], v[182:185], off
	global_store_dwordx4 v[178:179], v[244:247], off
	s_waitcnt lgkmcnt(0)
; DI unsigned pk2(float lo, float hi) { return pg8::cvt_pk_bf16(lo, hi); }
;     DI void operator()(const f32x4 (&acc)[2][2][4][2], const Unit& u, int wr, int wc, int fr, int fq) const {
;     ...
;             for (int m = 0; m < 4; ++m) { const size_t r = (size_t)(row0 + ai * 128 + m * 16); float ss = 0.f;
; #pragma unroll
;                 for (int bj = 0; bj < 2; ++bj) { const size_t off = r * 1024 + col0 + bj * 128;
;                     f32x4 v0 = *(const f32x4*)(base + off), v1 = *(const f32x4*)(base + off + 4);
;                     v0 += g[bj][0] * acc[ai][bj][m][0]; v1 += g[bj][1] * acc[ai][bj][m][1];
;                     *(f32x4*)(out + off) = v0; *(f32x4*)(out + off + 4) = v1;
;                     ss += (v0[0] * v0[0] + v0[1] * v0[1]) + (v0[2] * v0[2] + v0[3] * v0[3]) + (v1[0] * v1[0] + v1[1] * v1[1]) + (v1[2] * v1[2] + v1[3] * v1[3]);
;                     const f32x4 u0 = v0 * gm[bj][0], u1 = v1 * gm[bj][1];
;                     v4u w; w.x = pk2(u0[0], u0[1]); w.y = pk2(u0[2], u0[3]); w.z = pk2(u1[0], u1[1]); w.w = pk2(u1[2], u1[3]);
;                     *(v4u*)(U2 + off) = w; }
;                 ss += __shfl_xor(ss, 16); ss += __shfl_xor(ss, 32);
;                 if (fq == 0) atomicAdd(rowss + r, ss); }
	v_add_f32_e32 v248, v248, v201
	s_and_saveexec_b64 s[26:27], s[4:5]
	global_atomic_add_f32 v[160:161], v248, off offset:512
	s_or_b64 exec, exec, s[26:27]
	s_waitcnt vmcnt(7)
	v_mov_b32_e32 v234, v218
	v_mov_b32_e32 v235, v219
	v_mov_b32_e32 v236, v220
	v_mov_b32_e32 v237, v221
	v_mov_b32_dpp v218, v222 row_shr:8 row_mask:0xf bank_mask:0xc
	v_mov_b32_dpp v219, v223 row_shr:8 row_mask:0xf bank_mask:0xc
	v_mov_b32_dpp v220, v224 row_shr:8 row_mask:0xf bank_mask:0xc
	v_mov_b32_dpp v221, v225 row_shr:8 row_mask:0xf bank_mask:0xc
	v_mov_b32_dpp v222, v234 row_shl:8 row_mask:0xf bank_mask:0x3
	v_mov_b32_dpp v223, v235 row_shl:8 row_mask:0xf bank_mask:0x3
	v_mov_b32_dpp v224, v236 row_shl:8 row_mask:0xf bank_mask:0x3
	v_mov_b32_dpp v225, v237 row_shl:8 row_mask:0xf bank_mask:0x3
	v_mov_b32_e32 v234, v226
	v_mov_b32_e32 v235, v227
	v_mov_b32_e32 v236, v228
	v_mov_b32_e32 v237, v229
	v_mov_b32_dpp v226, v230 row_shr:8 row_mask:0xf bank_mask:0xc
	v_mov_b32_dpp v227, v231 row_shr:8 row_mask:0xf bank_mask:0xc
	v_mov_b32_dpp v228, v232 row_shr:8 row_mask:0xf bank_mask:0xc
	v_mov_b32_dpp v229, v233 row_shr:8 row_mask:0xf bank_mask:0xc
	v_mov_b32_dpp v230, v234 row_shl:8 row_mask:0xf bank_mask:0x3
	v_mov_b32_dpp v231, v235 row_shl:8 row_mask:0xf bank_mask:0x3
	v_mov_b32_dpp v232, v236 row_shl:8 row_mask:0xf bank_mask:0x3
	v_mov_b32_dpp v233, v237 row_shl:8 row_mask:0xf bank_mask:0x3
	v_pk_fma_f32 v[46:47], v[46:47], v[82:83], v[218:219]
	v_pk_fma_f32 v[48:49], v[48:49], v[84:85], v[220:221]
	v_pk_fma_f32 v[42:43], v[42:43], v[86:87], v[222:223]
	v_pk_fma_f32 v[44:45], v[44:45], v[88:89], v[224:225]
	v_pk_fma_f32 v[38:39], v[38:39], v[90:91], v[226:227]
	v_pk_fma_f32 v[40:41], v[40:41], v[92:93], v[228:229]
	v_pk_fma_f32 v[34:35], v[34:35], v[94:95], v[230:231]
	v_pk_fma_f32 v[36:37], v[36:37], v[96:97], v[232:233]
	v_mul_f32_e32 v218, v47, v47
	v_mul_f32_e32 v219, v49, v49
	v_mul_f32_e32 v220, v43, v43
	v_mul_f32_e32 v221, v45, v45
	v_fmac_f32_e32 v218, v46, v46
	v_fmac_f32_e32 v219, v48, v48
	v_fmac_f32_e32 v220, v42, v42
	v_fmac_f32_e32 v221, v44, v44
	v_add_f32_e32 v218, v218, v219
	v_add_f32_e32 v218, v218, v220
	v_add_f32_e32 v218, v221, v218
	v_mul_f32_e32 v222, v39, v39
	v_mul_f32_e32 v223, v41, v41
	v_mul_f32_e32 v224, v35, v35
	v_mul_f32_e32 v225, v37, v37
	v_fmac_f32_e32 v222, v38, v38
	v_fmac_f32_e32 v223, v40, v40
	v_fmac_f32_e32 v224, v34, v34
	v_fmac_f32_e32 v225, v36, v36
	v_add_f32_e32 v222, v222, v223
	v_add_f32_e32 v222, v222, v224
	v_add_f32_e32 v222, v225, v222
	v_add_f32_e32 v248, v218, v222
	ds_bpermute_b32 v201, v180, v248
	v_pk_mul_f32 v[218:219], v[202:203], v[46:47]
	v_pk_mul_f32 v[220:221], v[204:205], v[48:49]
	v_pk_mul_f32 v[222:223], v[206:207], v[42:43]
	v_pk_mul_f32 v[224:225], v[208:209], v[44:45]
	v_pk_mul_f32 v[226:227], v[210:211], v[38:39]
	v_pk_mul_f32 v[228:229], v[212:213], v[40:41]
	v_pk_mul_f32 v[230:231], v[214:215], v[34:35]
	v_pk_mul_f32 v[232:233], v[216:217], v[36:37]
	v_cvt_pk_bf16_f32 v182, v218, v219
	v_cvt_pk_bf16_f32 v183, v220, v221
	v_cvt_pk_bf16_f32 v184, v222, v223
	v_cvt_pk_bf16_f32 v185, v224, v225
	v_cvt_pk_bf16_f32 v244, v226, v227
	v_cvt_pk_bf16_f32 v245, v228, v229
	v_cvt_pk_bf16_f32 v246, v230, v231
	v_cvt_pk_bf16_f32 v247, v232, v233
	s_waitcnt lgkmcnt(0)
	v_add_f32_e32 v248, v248, v201
	ds_bpermute_b32 v201, v181, v248
	v_mov_b32_e32 v234, v244
	v_mov_b32_e32 v235, v245
	v_mov_b32_e32 v236, v246
	v_mov_b32_e32 v237, v247
	v_mov_b32_dpp v244, v182 row_shl:8 row_mask:0xf bank_mask:0x3
	v_mov_b32_dpp v245, v183 row_shl:8 row_mask:0xf bank_mask:0x3
	v_mov_b32_dpp v246, v184 row_shl:8 row_mask:0xf bank_mask:0x3
	v_mov_b32_dpp v247, v185 row_shl:8 row_mask:0xf bank_mask:0x3
	v_mov_b32_dpp v182, v234 row_shr:8 row_mask:0xf bank_mask:0xc
	v_mov_b32_dpp v183, v235 row_shr:8 row_mask:0xf bank_mask:0xc
	v_mov_b32_dpp v184, v236 row_shr:8 row_mask:0xf bank_mask:0xc
	v_mov_b32_dpp v185, v237 row_shr:8 row_mask:0xf bank_mask:0xc
	v_mov_b32_e32 v234, v42
	v_mov_b32_e32 v235, v43
	v_mov_b32_e32 v236, v44
	v_mov_b32_e32 v237, v45
	v_mov_b32_dpp v42, v46 row_shl:8 row_mask:0xf bank_mask:0x3
	v_mov_b32_dpp v43, v47 row_shl:8 row_mask:0xf bank_mask:0x3
	v_mov_b32_dpp v44, v48 row_shl:8 row_mask:0xf bank_mask:0x3
	v_mov_b32_dpp v45, v49 row_shl:8 row_mask:0xf bank_mask:0x3
	v_mov_b32_dpp v46, v234 row_shr:8 row_mask:0xf bank_mask:0xc
	v_mov_b32_dpp v47, v235 row_shr:8 row_mask:0xf bank_mask:0xc
	v_mov_b32_dpp v48, v236 row_shr:8 row_mask:0xf bank_mask:0xc
	v_mov_b32_dpp v49, v237 row_shr:8 row_mask:0xf bank_mask:0xc
	v_mov_b32_e32 v234, v34
	v_mov_b32_e32 v235, v35
	v_mov_b32_e32 v236, v36
	v_mov_b32_e32 v237, v37
	v_mov_b32_dpp v34, v38 row_shl:8 row_mask:0xf bank_mask:0x3
	v_mov_b32_dpp v35, v39 row_shl:8 row_mask:0xf bank_mask:0x3
	v_mov_b32_dpp v36, v40 row_shl:8 row_mask:0xf bank_mask:0x3
	v_mov_b32_dpp v37, v41 row_shl:8 row_mask:0xf bank_mask:0x3
	v_mov_b32_dpp v38, v234 row_shr:8 row_mask:0xf bank_mask:0xc
	v_mov_b32_dpp v39, v235 row_shr:8 row_mask:0xf bank_mask:0xc
	v_mov_b32_dpp v40, v236 row_shr:8 row_mask:0xf bank_mask:0xc
	v_mov_b32_dpp v41, v237 row_shr:8 row_mask:0xf bank_mask:0xc
	s_mov_b64 s[98:99], 0xa0000
	v_lshl_add_u64 v[162:163], v[156:157], 0, s[98:99]
	s_mov_b64 s[98:99], 0xa8000
	v_lshl_add_u64 v[164:165], v[156:157], 0, s[98:99]
	global_load_dwordx4 v[218:221], v[162:163], off
	global_load_dwordx4 v[222:225], v[164:165], off
	global_load_dwordx4 v[226:229], v[162:163], off offset:128
	global_load_dwordx4 v[230:233], v[164:165], off offset:128
	s_add_u32 s98, s100, 0x90000
	s_addc_u32 s99, s101, 0
	v_lshl_add_u64 v[190:191], v[156:157], 0, s[98:99]
	s_add_u32 s98, s100, 0x98000
	s_addc_u32 s99, s101, 0
	v_lshl_add_u64 v[178:179], v[156:157], 0, s[98:99]
	global_store_dwordx4 v[190:191], v[46:49], off
	global_store_dwordx4 v[178:179], v[42:45], off
	global_store_dwordx4 v[190:191], v[38:41], off offset:128
	global_store_dwordx4 v[178:179], v[34:37], off offset:128
	s_mov_b64 s[98:99], 0x48000
	v_lshl_add_u64 v[190:191], v[158:159], 0, s[98:99]
	s_mov_b64 s[98:99], 0x4c000
	v_lshl_add_u64 v[178:179], v[158:159], 0, s[98:99]
	global_store_dwordx4 v[190:191], v[182:185], off
	global_store_dwordx4 v[178:179], v[244:247], off
	s_waitcnt lgkmcnt(0)
; DI unsigned pk2(float lo, float hi) { return pg8::cvt_pk_bf16(lo, hi); }
;     DI void operator()(const f32x4 (&acc)[2][2][4][2], const Unit& u, int wr, int wc, int fr, int fq) const {
;     ...
;             for (int m = 0; m < 4; ++m) { const size_t r = (size_t)(row0 + ai * 128 + m * 16); float ss = 0.f;
; #pragma unroll
;                 for (int bj = 0; bj < 2; ++bj) { const size_t off = r * 1024 + col0 + bj * 128;
;                     f32x4 v0 = *(const f32x4*)(base + off), v1 = *(const f32x4*)(base + off + 4);
;                     v0 += g[bj][0] * acc[ai][bj][m][0]; v1 += g[bj][1] * acc[ai][bj][m][1];
;                     *(f32x4*)(out + off) = v0; *(f32x4*)(out + off + 4) = v1;
;                     ss += (v0[0] * v0[0] + v0[1] * v0[1]) + (v0[2] * v0[2] + v0[3] * v0[3]) + (v1[0] * v1[0] + v1[1] * v1[1]) + (v1[2] * v1[2] + v1[3] * v1[3]);
;                     const f32x4 u0 = v0 * gm[bj][0], u1 = v1 * gm[bj][1];
;                     v4u w; w.x = pk2(u0[0], u0[1]); w.y = pk2(u0[2], u0[3]); w.z = pk2(u1[0], u1[1]); w.w = pk2(u1[2], u1[3]);
;                     *(v4u*)(U2 + off) = w; }
;                 ss += __shfl_xor(ss, 16); ss += __shfl_xor(ss, 32);
;                 if (fq == 0) atomicAdd(rowss + r, ss); }
	v_add_f32_e32 v248, v248, v201
	s_and_saveexec_b64 s[26:27], s[4:5]
	global_atomic_add_f32 v[160:161], v248, off offset:576
	s_or_b64 exec, exec, s[26:27]
	s_waitcnt vmcnt(7)
	v_mov_b32_e32 v234, v218
	v_mov_b32_e32 v235, v219
	v_mov_b32_e32 v236, v220
	v_mov_b32_e32 v237, v221
	v_mov_b32_dpp v218, v222 row_shr:8 row_mask:0xf bank_mask:0xc
	v_mov_b32_dpp v219, v223 row_shr:8 row_mask:0xf bank_mask:0xc
	v_mov_b32_dpp v220, v224 row_shr:8 row_mask:0xf bank_mask:0xc
	v_mov_b32_dpp v221, v225 row_shr:8 row_mask:0xf bank_mask:0xc
	v_mov_b32_dpp v222, v234 row_shl:8 row_mask:0xf bank_mask:0x3
	v_mov_b32_dpp v223, v235 row_shl:8 row_mask:0xf bank_mask:0x3
	v_mov_b32_dpp v224, v236 row_shl:8 row_mask:0xf bank_mask:0x3
	v_mov_b32_dpp v225, v237 row_shl:8 row_mask:0xf bank_mask:0x3
	v_mov_b32_e32 v234, v226
	v_mov_b32_e32 v235, v227
	v_mov_b32_e32 v236, v228
	v_mov_b32_e32 v237, v229
	v_mov_b32_dpp v226, v230 row_shr:8 row_mask:0xf bank_mask:0xc
	v_mov_b32_dpp v227, v231 row_shr:8 row_mask:0xf bank_mask:0xc
	v_mov_b32_dpp v228, v232 row_shr:8 row_mask:0xf bank_mask:0xc
	v_mov_b32_dpp v229, v233 row_shr:8 row_mask:0xf bank_mask:0xc
	v_mov_b32_dpp v230, v234 row_shl:8 row_mask:0xf bank_mask:0x3
	v_mov_b32_dpp v231, v235 row_shl:8 row_mask:0xf bank_mask:0x3
	v_mov_b32_dpp v232, v236 row_shl:8 row_mask:0xf bank_mask:0x3
	v_mov_b32_dpp v233, v237 row_shl:8 row_mask:0xf bank_mask:0x3
	v_pk_fma_f32 v[30:31], v[30:31], v[82:83], v[218:219]
	v_pk_fma_f32 v[32:33], v[32:33], v[84:85], v[220:221]
	v_pk_fma_f32 v[26:27], v[26:27], v[86:87], v[222:223]
	v_pk_fma_f32 v[28:29], v[28:29], v[88:89], v[224:225]
	v_pk_fma_f32 v[22:23], v[22:23], v[90:91], v[226:227]
	v_pk_fma_f32 v[24:25], v[24:25], v[92:93], v[228:229]
	v_pk_fma_f32 v[18:19], v[18:19], v[94:95], v[230:231]
	v_pk_fma_f32 v[20:21], v[20:21], v[96:97], v[232:233]
	v_mul_f32_e32 v218, v31, v31
	v_mul_f32_e32 v219, v33, v33
	v_mul_f32_e32 v220, v27, v27
	v_mul_f32_e32 v221, v29, v29
	v_fmac_f32_e32 v218, v30, v30
	v_fmac_f32_e32 v219, v32, v32
	v_fmac_f32_e32 v220, v26, v26
	v_fmac_f32_e32 v221, v28, v28
	v_add_f32_e32 v218, v218, v219
	v_add_f32_e32 v218, v218, v220
	v_add_f32_e32 v218, v221, v218
	v_mul_f32_e32 v222, v23, v23
	v_mul_f32_e32 v223, v25, v25
	v_mul_f32_e32 v224, v19, v19
	v_mul_f32_e32 v225, v21, v21
	v_fmac_f32_e32 v222, v22, v22
	v_fmac_f32_e32 v223, v24, v24
	v_fmac_f32_e32 v224, v18, v18
	v_fmac_f32_e32 v225, v20, v20
	v_add_f32_e32 v222, v222, v223
	v_add_f32_e32 v222, v222, v224
	v_add_f32_e32 v222, v225, v222
	v_add_f32_e32 v248, v218, v222
	ds_bpermute_b32 v201, v180, v248
	v_pk_mul_f32 v[218:219], v[202:203], v[30:31]
	v_pk_mul_f32 v[220:221], v[204:205], v[32:33]
	v_pk_mul_f32 v[222:223], v[206:207], v[26:27]
	v_pk_mul_f32 v[224:225], v[208:209], v[28:29]
	v_pk_mul_f32 v[226:227], v[210:211], v[22:23]
	v_pk_mul_f32 v[228:229], v[212:213], v[24:25]
	v_pk_mul_f32 v[230:231], v[214:215], v[18:19]
	v_pk_mul_f32 v[232:233], v[216:217], v[20:21]
	v_cvt_pk_bf16_f32 v182, v218, v219
	v_cvt_pk_bf16_f32 v183, v220, v221
	v_cvt_pk_bf16_f32 v184, v222, v223
	v_cvt_pk_bf16_f32 v185, v224, v225
	v_cvt_pk_bf16_f32 v244, v226, v227
	v_cvt_pk_bf16_f32 v245, v228, v229
	v_cvt_pk_bf16_f32 v246, v230, v231
	v_cvt_pk_bf16_f32 v247, v232, v233
	s_waitcnt lgkmcnt(0)
	v_add_f32_e32 v248, v248, v201
	ds_bpermute_b32 v201, v181, v248
	v_mov_b32_e32 v234, v244
	v_mov_b32_e32 v235, v245
	v_mov_b32_e32 v236, v246
	v_mov_b32_e32 v237, v247
	v_mov_b32_dpp v244, v182 row_shl:8 row_mask:0xf bank_mask:0x3
	v_mov_b32_dpp v245, v183 row_shl:8 row_mask:0xf bank_mask:0x3
	v_mov_b32_dpp v246, v184 row_shl:8 row_mask:0xf bank_mask:0x3
	v_mov_b32_dpp v247, v185 row_shl:8 row_mask:0xf bank_mask:0x3
	v_mov_b32_dpp v182, v234 row_shr:8 row_mask:0xf bank_mask:0xc
	v_mov_b32_dpp v183, v235 row_shr:8 row_mask:0xf bank_mask:0xc
	v_mov_b32_dpp v184, v236 row_shr:8 row_mask:0xf bank_mask:0xc
	v_mov_b32_dpp v185, v237 row_shr:8 row_mask:0xf bank_mask:0xc
	v_mov_b32_e32 v234, v26
	v_mov_b32_e32 v235, v27
	v_mov_b32_e32 v236, v28
	v_mov_b32_e32 v237, v29
	v_mov_b32_dpp v26, v30 row_shl:8 row_mask:0xf bank_mask:0x3
	v_mov_b32_dpp v27, v31 row_shl:8 row_mask:0xf bank_mask:0x3
	v_mov_b32_dpp v28, v32 row_shl:8 row_mask:0xf bank_mask:0x3
	v_mov_b32_dpp v29, v33 row_shl:8 row_mask:0xf bank_mask:0x3
	v_mov_b32_dpp v30, v234 row_shr:8 row_mask:0xf bank_mask:0xc
	v_mov_b32_dpp v31, v235 row_shr:8 row_mask:0xf bank_mask:0xc
	v_mov_b32_dpp v32, v236 row_shr:8 row_mask:0xf bank_mask:0xc
	v_mov_b32_dpp v33, v237 row_shr:8 row_mask:0xf bank_mask:0xc
	v_mov_b32_e32 v234, v18
	v_mov_b32_e32 v235, v19
	v_mov_b32_e32 v236, v20
	v_mov_b32_e32 v237, v21
	v_mov_b32_dpp v18, v22 row_shl:8 row_mask:0xf bank_mask:0x3
	v_mov_b32_dpp v19, v23 row_shl:8 row_mask:0xf bank_mask:0x3
	v_mov_b32_dpp v20, v24 row_shl:8 row_mask:0xf bank_mask:0x3
	v_mov_b32_dpp v21, v25 row_shl:8 row_mask:0xf bank_mask:0x3
	v_mov_b32_dpp v22, v234 row_shr:8 row_mask:0xf bank_mask:0xc
	v_mov_b32_dpp v23, v235 row_shr:8 row_mask:0xf bank_mask:0xc
	v_mov_b32_dpp v24, v236 row_shr:8 row_mask:0xf bank_mask:0xc
	v_mov_b32_dpp v25, v237 row_shr:8 row_mask:0xf bank_mask:0xc
	s_mov_b64 s[98:99], 0xb0000
	v_lshl_add_u64 v[162:163], v[156:157], 0, s[98:99]
	s_mov_b64 s[98:99], 0xb8000
	v_lshl_add_u64 v[164:165], v[156:157], 0, s[98:99]
	global_load_dwordx4 v[218:221], v[162:163], off
	global_load_dwordx4 v[222:225], v[164:165], off
	global_load_dwordx4 v[226:229], v[162:163], off offset:128
	global_load_dwordx4 v[230:233], v[164:165], off offset:128
	s_add_u32 s98, s100, 0xa0000
	s_addc_u32 s99, s101, 0
	v_lshl_add_u64 v[190:191], v[156:157], 0, s[98:99]
	s_add_u32 s98, s100, 0xa8000
	s_addc_u32 s99, s101, 0
	v_lshl_add_u64 v[178:179], v[156:157], 0, s[98:99]
	global_store_dwordx4 v[190:191], v[30:33], off
	global_store_dwordx4 v[178:179], v[26:29], off
	global_store_dwordx4 v[190:191], v[22:25], off offset:128
	global_store_dwordx4 v[178:179], v[18:21], off offset:128
	s_mov_b64 s[98:99], 0x50000
	v_lshl_add_u64 v[190:191], v[158:159], 0, s[98:99]
	s_mov_b64 s[98:99], 0x54000
	v_lshl_add_u64 v[178:179], v[158:159], 0, s[98:99]
	global_store_dwordx4 v[190:191], v[182:185], off
	global_store_dwordx4 v[178:179], v[244:247], off
	s_waitcnt lgkmcnt(0)
; DI unsigned pk2(float lo, float hi) { return pg8::cvt_pk_bf16(lo, hi); }
;     DI void operator()(const f32x4 (&acc)[2][2][4][2], const Unit& u, int wr, int wc, int fr, int fq) const {
;     ...
;             for (int m = 0; m < 4; ++m) { const size_t r = (size_t)(row0 + ai * 128 + m * 16); float ss = 0.f;
; #pragma unroll
;                 for (int bj = 0; bj < 2; ++bj) { const size_t off = r * 1024 + col0 + bj * 128;
;                     f32x4 v0 = *(const f32x4*)(base + off), v1 = *(const f32x4*)(base + off + 4);
;                     v0 += g[bj][0] * acc[ai][bj][m][0]; v1 += g[bj][1] * acc[ai][bj][m][1];
;                     *(f32x4*)(out + off) = v0; *(f32x4*)(out + off + 4) = v1;
;                     ss += (v0[0] * v0[0] + v0[1] * v0[1]) + (v0[2] * v0[2] + v0[3] * v0[3]) + (v1[0] * v1[0] + v1[1] * v1[1]) + (v1[2] * v1[2] + v1[3] * v1[3]);
;                     const f32x4 u0 = v0 * gm[bj][0], u1 = v1 * gm[bj][1];
;                     v4u w; w.x = pk2(u0[0], u0[1]); w.y = pk2(u0[2], u0[3]); w.z = pk2(u1[0], u1[1]); w.w = pk2(u1[2], u1[3]);
;                     *(v4u*)(U2 + off) = w; }
;                 ss += __shfl_xor(ss, 16); ss += __shfl_xor(ss, 32);
;                 if (fq == 0) atomicAdd(rowss + r, ss); }
;     }
	v_add_f32_e32 v248, v248, v201
	s_and_saveexec_b64 s[26:27], s[4:5]
	global_atomic_add_f32 v[160:161], v248, off offset:640
	s_or_b64 exec, exec, s[26:27]
	s_waitcnt vmcnt(7)
	v_mov_b32_e32 v234, v218
	v_mov_b32_e32 v235, v219
	v_mov_b32_e32 v236, v220
	v_mov_b32_e32 v237, v221
	v_mov_b32_dpp v218, v222 row_shr:8 row_mask:0xf bank_mask:0xc
	v_mov_b32_dpp v219, v223 row_shr:8 row_mask:0xf bank_mask:0xc
	v_mov_b32_dpp v220, v224 row_shr:8 row_mask:0xf bank_mask:0xc
	v_mov_b32_dpp v221, v225 row_shr:8 row_mask:0xf bank_mask:0xc
	v_mov_b32_dpp v222, v234 row_shl:8 row_mask:0xf bank_mask:0x3
	v_mov_b32_dpp v223, v235 row_shl:8 row_mask:0xf bank_mask:0x3
	v_mov_b32_dpp v224, v236 row_shl:8 row_mask:0xf bank_mask:0x3
	v_mov_b32_dpp v225, v237 row_shl:8 row_mask:0xf bank_mask:0x3
	v_mov_b32_e32 v234, v226
	v_mov_b32_e32 v235, v227
	v_mov_b32_e32 v236, v228
	v_mov_b32_e32 v237, v229
	v_mov_b32_dpp v226, v230 row_shr:8 row_mask:0xf bank_mask:0xc
	v_mov_b32_dpp v227, v231 row_shr:8 row_mask:0xf bank_mask:0xc
	v_mov_b32_dpp v228, v232 row_shr:8 row_mask:0xf bank_mask:0xc
	v_mov_b32_dpp v229, v233 row_shr:8 row_mask:0xf bank_mask:0xc
	v_mov_b32_dpp v230, v234 row_shl:8 row_mask:0xf bank_mask:0x3
	v_mov_b32_dpp v231, v235 row_shl:8 row_mask:0xf bank_mask:0x3
	v_mov_b32_dpp v232, v236 row_shl:8 row_mask:0xf bank_mask:0x3
	v_mov_b32_dpp v233, v237 row_shl:8 row_mask:0xf bank_mask:0x3
	v_pk_fma_f32 v[14:15], v[14:15], v[82:83], v[218:219]
	v_pk_fma_f32 v[16:17], v[16:17], v[84:85], v[220:221]
	v_pk_fma_f32 v[10:11], v[10:11], v[86:87], v[222:223]
	v_pk_fma_f32 v[12:13], v[12:13], v[88:89], v[224:225]
	v_pk_fma_f32 v[6:7], v[6:7], v[90:91], v[226:227]
	v_pk_fma_f32 v[8:9], v[8:9], v[92:93], v[228:229]
	v_pk_fma_f32 v[2:3], v[2:3], v[94:95], v[230:231]
	v_pk_fma_f32 v[4:5], v[4:5], v[96:97], v[232:233]
	v_mul_f32_e32 v218, v15, v15
	v_mul_f32_e32 v219, v17, v17
	v_mul_f32_e32 v220, v11, v11
	v_mul_f32_e32 v221, v13, v13
	v_fmac_f32_e32 v218, v14, v14
	v_fmac_f32_e32 v219, v16, v16
	v_fmac_f32_e32 v220, v10, v10
	v_fmac_f32_e32 v221, v12, v12
	v_add_f32_e32 v218, v218, v219
	v_add_f32_e32 v218, v218, v220
	v_add_f32_e32 v218, v221, v218
	v_mul_f32_e32 v222, v7, v7
	v_mul_f32_e32 v223, v9, v9
	v_mul_f32_e32 v224, v3, v3
	v_mul_f32_e32 v225, v5, v5
	v_fmac_f32_e32 v222, v6, v6
	v_fmac_f32_e32 v223, v8, v8
	v_fmac_f32_e32 v224, v2, v2
	v_fmac_f32_e32 v225, v4, v4
	v_add_f32_e32 v222, v222, v223
	v_add_f32_e32 v222, v222, v224
	v_add_f32_e32 v222, v225, v222
	v_add_f32_e32 v248, v218, v222
	ds_bpermute_b32 v201, v180, v248
	v_pk_mul_f32 v[218:219], v[202:203], v[14:15]
	v_pk_mul_f32 v[220:221], v[204:205], v[16:17]
	v_pk_mul_f32 v[222:223], v[206:207], v[10:11]
	v_pk_mul_f32 v[224:225], v[208:209], v[12:13]
	v_pk_mul_f32 v[226:227], v[210:211], v[6:7]
	v_pk_mul_f32 v[228:229], v[212:213], v[8:9]
	v_pk_mul_f32 v[230:231], v[214:215], v[2:3]
	v_pk_mul_f32 v[232:233], v[216:217], v[4:5]
	v_cvt_pk_bf16_f32 v182, v218, v219
	v_cvt_pk_bf16_f32 v183, v220, v221
	v_cvt_pk_bf16_f32 v184, v222, v223
	v_cvt_pk_bf16_f32 v185, v224, v225
	v_cvt_pk_bf16_f32 v244, v226, v227
	v_cvt_pk_bf16_f32 v245, v228, v229
	v_cvt_pk_bf16_f32 v246, v230, v231
	v_cvt_pk_bf16_f32 v247, v232, v233
	s_waitcnt lgkmcnt(0)
	v_add_f32_e32 v248, v248, v201
	ds_bpermute_b32 v201, v181, v248
	v_mov_b32_e32 v234, v244
	v_mov_b32_e32 v235, v245
	v_mov_b32_e32 v236, v246
	v_mov_b32_e32 v237, v247
	v_mov_b32_dpp v244, v182 row_shl:8 row_mask:0xf bank_mask:0x3
	v_mov_b32_dpp v245, v183 row_shl:8 row_mask:0xf bank_mask:0x3
	v_mov_b32_dpp v246, v184 row_shl:8 row_mask:0xf bank_mask:0x3
	v_mov_b32_dpp v247, v185 row_shl:8 row_mask:0xf bank_mask:0x3
	v_mov_b32_dpp v182, v234 row_shr:8 row_mask:0xf bank_mask:0xc
	v_mov_b32_dpp v183, v235 row_shr:8 row_mask:0xf bank_mask:0xc
	v_mov_b32_dpp v184, v236 row_shr:8 row_mask:0xf bank_mask:0xc
	v_mov_b32_dpp v185, v237 row_shr:8 row_mask:0xf bank_mask:0xc
	v_mov_b32_e32 v234, v10
	v_mov_b32_e32 v235, v11
	v_mov_b32_e32 v236, v12
	v_mov_b32_e32 v237, v13
	v_mov_b32_dpp v10, v14 row_shl:8 row_mask:0xf bank_mask:0x3
	v_mov_b32_dpp v11, v15 row_shl:8 row_mask:0xf bank_mask:0x3
	v_mov_b32_dpp v12, v16 row_shl:8 row_mask:0xf bank_mask:0x3
	v_mov_b32_dpp v13, v17 row_shl:8 row_mask:0xf bank_mask:0x3
	v_mov_b32_dpp v14, v234 row_shr:8 row_mask:0xf bank_mask:0xc
	v_mov_b32_dpp v15, v235 row_shr:8 row_mask:0xf bank_mask:0xc
	v_mov_b32_dpp v16, v236 row_shr:8 row_mask:0xf bank_mask:0xc
	v_mov_b32_dpp v17, v237 row_shr:8 row_mask:0xf bank_mask:0xc
	v_mov_b32_e32 v234, v2
	v_mov_b32_e32 v235, v3
	v_mov_b32_e32 v236, v4
	v_mov_b32_e32 v237, v5
	v_mov_b32_dpp v2, v6 row_shl:8 row_mask:0xf bank_mask:0x3
	v_mov_b32_dpp v3, v7 row_shl:8 row_mask:0xf bank_mask:0x3
	v_mov_b32_dpp v4, v8 row_shl:8 row_mask:0xf bank_mask:0x3
	v_mov_b32_dpp v5, v9 row_shl:8 row_mask:0xf bank_mask:0x3
	v_mov_b32_dpp v6, v234 row_shr:8 row_mask:0xf bank_mask:0xc
	v_mov_b32_dpp v7, v235 row_shr:8 row_mask:0xf bank_mask:0xc
	v_mov_b32_dpp v8, v236 row_shr:8 row_mask:0xf bank_mask:0xc
	v_mov_b32_dpp v9, v237 row_shr:8 row_mask:0xf bank_mask:0xc
	s_add_u32 s98, s100, 0xb0000
	s_addc_u32 s99, s101, 0
	v_lshl_add_u64 v[190:191], v[156:157], 0, s[98:99]
	s_add_u32 s98, s100, 0xb8000
	s_addc_u32 s99, s101, 0
	v_lshl_add_u64 v[178:179], v[156:157], 0, s[98:99]
	global_store_dwordx4 v[190:191], v[14:17], off
	global_store_dwordx4 v[178:179], v[10:13], off
	global_store_dwordx4 v[190:191], v[6:9], off offset:128
	global_store_dwordx4 v[178:179], v[2:5], off offset:128
	s_mov_b64 s[98:99], 0x58000
	v_lshl_add_u64 v[190:191], v[158:159], 0, s[98:99]
	s_mov_b64 s[98:99], 0x5c000
	v_lshl_add_u64 v[178:179], v[158:159], 0, s[98:99]
	global_store_dwordx4 v[190:191], v[182:185], off
	global_store_dwordx4 v[178:179], v[244:247], off
	s_waitcnt lgkmcnt(0)
	v_add_f32_e32 v248, v248, v201
	s_and_saveexec_b64 s[26:27], s[4:5]
	global_atomic_add_f32 v[160:161], v248, off offset:704
	s_or_b64 exec, exec, s[26:27]
	v_readlane_b32 s30, v254, 34
	v_readlane_b32 s31, v254, 35
	v_readlane_b32 s48, v254, 36
	v_readlane_b32 s49, v254, 37
	v_readlane_b32 s50, v254, 38
	s_andn2_b64 vcc, exec, s[6:7]
	s_mov_b64 s[6:7], -1
	s_cbranch_vccnz .LBB0_643
	s_andn2_b64 vcc, exec, s[2:3]
	s_cbranch_vccnz .LBB0_642
	s_barrier
	s_branch .LBB0_642
